# K-loops: each segment's vmcnt(N) and lgkmcnt(0) waits in front of the barrier merged into one s_waitcnt (16 fewer instructions per 4 loops' iteration); on top of v100
# speedup vs baseline: 1.0011x; 1.0011x over previous
; #define PG8_STAGE(bufoff, gbase, voff) do { _Pragma("unroll") for (int _i = 0; _i < 2; ++_i) \
;         __builtin_amdgcn_global_load_lds((const unsigned*)((const char*)(gbase) + (voff)[_i]), (PG8_LAS unsigned*)(lds + (bufoff) + ldsw + _i * 8192), 16, 0, 0); } while (0)
; #define PG8_LDA(dst, b, h) do { _Pragma("unroll") for (int m = 0; m < 4; ++m) _Pragma("unroll") for (int k = 0; k < 2; ++k) dst[m][k] = *(const PG8_LAS bf16x8*)(lds + PG8_SA(b, h) + aoff + m * 2048 + k * 1024); } while (0)
; #define PG8_WAIT_V(n) asm volatile("s_waitcnt vmcnt(" #n ")" ::: "memory")
; #define PG8_WAIT_L(n) asm volatile("s_waitcnt lgkmcnt(" #n ")" ::: "memory")
; #define PG8_BAR __builtin_amdgcn_s_barrier()
; #define PG8_SCHED __builtin_amdgcn_sched_barrier(0)
;     ...
;             PG8_WAIT_V(8); PG8_WAIT_L(0); PG8_BAR; PG8_MMA(0, 0, At, B0); PG8_MMA(0, 1, At, B1); PG8_BAR; PG8_SCHED;
;             PG8_LDA(At, 0, 1); PG8_STAGE(PG8_SB(0, 0), b2, voffB); PG8_STAGE(PG8_SB(0, 1), b2 + hstepB, voffB); PG8_STAGE(PG8_SA(0, 0), a2, voffA);
;             PG8_WAIT_V(8); PG8_WAIT_L(0); PG8_BAR; PG8_MMA(1, 0, At, B0); PG8_MMA(1, 1, At, B1); PG8_BAR; PG8_SCHED;
.Lpka_na:
	s_bcnt1_i32_b32 vcc_lo, s100
	s_cmp_eq_u32 vcc_lo, 0
	s_cbranch_scc1 .Lpka_w8a
	s_cmp_eq_u32 vcc_lo, 1
	s_cbranch_scc1 .Lpka_w9a
	s_waitcnt vmcnt(10) lgkmcnt(0)
	s_branch .Lpka_da
.Lpka_w9a:
	s_waitcnt vmcnt(9) lgkmcnt(0)
	s_branch .Lpka_da
.Lpka_w8a:
	s_waitcnt vmcnt(8) lgkmcnt(0)
.Lpka_da:
	s_barrier
	v_mfma_f32_16x16x32_bf16 v[132:135], v[144:147], v[210:213], v[132:135]
	v_mfma_f32_16x16x32_bf16 v[128:131], v[152:155], v[210:213], v[128:131]
	v_mfma_f32_16x16x32_bf16 v[116:119], v[144:147], v[218:221], v[116:119]
	v_mfma_f32_16x16x32_bf16 v[112:115], v[152:155], v[218:221], v[112:115]
	v_mfma_f32_16x16x32_bf16 v[100:103], v[144:147], v[226:229], v[100:103]
	v_mfma_f32_16x16x32_bf16 v[96:99], v[152:155], v[226:229], v[96:99]
	v_mfma_f32_16x16x32_bf16 v[84:87], v[144:147], v[234:237], v[84:87]
	v_mfma_f32_16x16x32_bf16 v[80:83], v[152:155], v[234:237], v[80:83]
	v_mfma_f32_16x16x32_bf16 v[132:135], v[148:151], v[214:217], v[132:135]
	v_mfma_f32_16x16x32_bf16 v[128:131], v[156:159], v[214:217], v[128:131]
	v_mfma_f32_16x16x32_bf16 v[116:119], v[148:151], v[222:225], v[116:119]
	v_mfma_f32_16x16x32_bf16 v[112:115], v[156:159], v[222:225], v[112:115]
	v_mfma_f32_16x16x32_bf16 v[100:103], v[148:151], v[230:233], v[100:103]
	v_mfma_f32_16x16x32_bf16 v[96:99], v[156:159], v[230:233], v[96:99]
	v_mfma_f32_16x16x32_bf16 v[84:87], v[148:151], v[238:241], v[84:87]
	v_mfma_f32_16x16x32_bf16 v[80:83], v[156:159], v[238:241], v[80:83]
	v_mfma_f32_16x16x32_bf16 v[140:143], v[186:189], v[210:213], v[140:143]
	v_mfma_f32_16x16x32_bf16 v[136:139], v[202:205], v[210:213], v[136:139]
	v_mfma_f32_16x16x32_bf16 v[124:127], v[186:189], v[218:221], v[124:127]
	v_mfma_f32_16x16x32_bf16 v[120:123], v[202:205], v[218:221], v[120:123]
	v_mfma_f32_16x16x32_bf16 v[108:111], v[186:189], v[226:229], v[108:111]
	v_mfma_f32_16x16x32_bf16 v[104:107], v[202:205], v[226:229], v[104:107]
	v_mfma_f32_16x16x32_bf16 v[92:95], v[186:189], v[234:237], v[92:95]
	v_mfma_f32_16x16x32_bf16 v[88:91], v[202:205], v[234:237], v[88:91]
	v_mfma_f32_16x16x32_bf16 v[140:143], v[198:201], v[214:217], v[140:143]
	v_mfma_f32_16x16x32_bf16 v[136:139], v[206:209], v[214:217], v[136:139]
	v_mfma_f32_16x16x32_bf16 v[124:127], v[198:201], v[222:225], v[124:127]
	v_mfma_f32_16x16x32_bf16 v[120:123], v[206:209], v[222:225], v[120:123]
	v_mfma_f32_16x16x32_bf16 v[108:111], v[198:201], v[230:233], v[108:111]
	v_mfma_f32_16x16x32_bf16 v[104:107], v[206:209], v[230:233], v[104:107]
	v_mfma_f32_16x16x32_bf16 v[92:95], v[198:201], v[238:241], v[92:95]
	v_mfma_f32_16x16x32_bf16 v[88:91], v[206:209], v[238:241], v[88:91]
	s_barrier
	s_add_i32 s82, s82, s15
	s_mov_b32 m0, s82
	ds_read_b128 v[210:213], v197 offset:16384
	ds_read_b128 v[214:217], v197 offset:17408
	ds_read_b128 v[218:221], v197 offset:18432
	ds_read_b128 v[222:225], v197 offset:19456
	ds_read_b128 v[226:229], v197 offset:20480
	ds_read_b128 v[230:233], v197 offset:21504
	ds_read_b128 v[234:237], v197 offset:22528
	ds_read_b128 v[238:241], v197 offset:23552
	global_load_lds_dwordx4 v170, s[72:73]
	s_add_i32 m0, s82, 0x2000
	s_add_u32 s82, s72, 0x10000
	s_addc_u32 s83, s73, 0
	s_add_i32 s86, s86, s15
	global_load_lds_dwordx4 v166, s[72:73]
	s_mov_b32 m0, s86
	s_nop 0
	global_load_lds_dwordx4 v170, s[82:83]
	s_add_i32 m0, s86, 0x2000
	s_nop 0
	global_load_lds_dwordx4 v166, s[82:83]
	s_mov_b32 m0, s63
	s_nop 0
	global_load_lds_dwordx4 v172, s[76:77]
	s_mov_b32 m0, s64
	s_nop 0
	global_load_lds_dwordx4 v168, s[76:77]
	s_lshl_b32 s100, s100, 1
	s_and_b32 s100, s100, 6
	s_bcnt1_i32_b32 vcc_lo, s100
	s_cmp_eq_u32 vcc_lo, 0
	s_cbranch_scc1 .Lpka_w8b
	s_cmp_eq_u32 vcc_lo, 1
	s_cbranch_scc1 .Lpka_w9b
	s_waitcnt vmcnt(10) lgkmcnt(0)
	s_branch .Lpka_db

; __device__ __forceinline__ void st16_wt(void* p, u32x4 v) { if (WT_STORES) asm volatile("global_store_dwordx4 %0, %1, off sc1\n\ts_nop 1" :: "v"(p), "v"(v) : "memory"); else *(u32x4*)p = v; }
; __device__ __forceinline__ unsigned cvt_pk_bf16(float lo, float hi) { unsigned r; asm volatile("v_cvt_pk_bf16_f32 %0, %1, %2" : "=v"(r) : "v"(lo), "v"(hi)); return r; }
; #define PG8_STAGE(bufoff, gbase, voff) do { _Pragma("unroll") for (int _i = 0; _i < 2; ++_i) \
;         __builtin_amdgcn_global_load_lds((const unsigned*)((const char*)(gbase) + (voff)[_i]), (PG8_LAS unsigned*)(lds + (bufoff) + ldsw + _i * 8192), 16, 0, 0); } while (0)
; #define PG8_LDA(dst, b, h) do { _Pragma("unroll") for (int m = 0; m < 4; ++m) _Pragma("unroll") for (int k = 0; k < 2; ++k) dst[m][k] = *(const PG8_LAS bf16x8*)(lds + PG8_SA(b, h) + aoff + m * 2048 + k * 1024); } while (0)
; #define PG8_LDB(dst, b, h) do { _Pragma("unroll") for (int n = 0; n < 2; ++n) _Pragma("unroll") for (int k = 0; k < 2; ++k) dst[n][k] = *(const PG8_LAS bf16x8*)(lds + PG8_SB(b, h) + boff + n * 2048 + k * 1024); } while (0)
; #define PG8_WAIT_V(n) asm volatile("s_waitcnt vmcnt(" #n ")" ::: "memory")
; #define PG8_WAIT_L(n) asm volatile("s_waitcnt lgkmcnt(" #n ")" ::: "memory")
; #define PG8_BAR __builtin_amdgcn_s_barrier()
; #define PG8_SCHED __builtin_amdgcn_sched_barrier(0)
;     __device__ __forceinline__ void operator()(const f32x4 (&acc)[2][2][4][2], const Unit& u, int wr, int wc, int fr, int fq, const bool reuse, PG8_LAS float* rscr, PG8_LAS const float* gains) const {
;     ...
;                 bf16_t* p = p0 + (size_t)(8 * ai + m) * step16;
; #pragma unroll
;                 for (int bj = 0; bj < 2; ++bj) { u32x4 w; w.x = cvt_pk_bf16(v[bj][0][0], v[bj][0][1]); w.y = cvt_pk_bf16(v[bj][0][2], v[bj][0][3]); w.z = cvt_pk_bf16(v[bj][1][0], v[bj][1][1]); w.w = cvt_pk_bf16(v[bj][1][2], v[bj][1][3]);
;                     st16_wt(p + 32 * bj, w); }
;     ...
;             PG8_WAIT_V(8); PG8_WAIT_L(0); PG8_BAR; PG8_MMA(1, 0, At, B0); PG8_MMA(1, 1, At, B1); PG8_BAR; PG8_SCHED;
;             PG8_LDB(B0, 1, 0); PG8_LDB(B1, 1, 1); PG8_SCHED; PG8_LDA(At, 1, 0); PG8_STAGE(PG8_SA(0, 1), a2 + hstep, voffA);
.Lpka_db:
	s_barrier
	v_mfma_f32_16x16x32_bf16 v[68:71], v[144:147], v[210:213], v[68:71]
	v_mfma_f32_16x16x32_bf16 v[64:67], v[152:155], v[210:213], v[64:67]
	v_mfma_f32_16x16x32_bf16 v[52:55], v[144:147], v[218:221], v[52:55]
	v_mfma_f32_16x16x32_bf16 v[48:51], v[152:155], v[218:221], v[48:51]
	v_mfma_f32_16x16x32_bf16 v[36:39], v[144:147], v[226:229], v[36:39]
	v_mfma_f32_16x16x32_bf16 v[32:35], v[152:155], v[226:229], v[32:35]
	v_mfma_f32_16x16x32_bf16 v[20:23], v[144:147], v[234:237], v[20:23]
	v_mfma_f32_16x16x32_bf16 v[16:19], v[152:155], v[234:237], v[16:19]
	v_mfma_f32_16x16x32_bf16 v[68:71], v[148:151], v[214:217], v[68:71]
	v_mfma_f32_16x16x32_bf16 v[64:67], v[156:159], v[214:217], v[64:67]
	v_mfma_f32_16x16x32_bf16 v[52:55], v[148:151], v[222:225], v[52:55]
	v_mfma_f32_16x16x32_bf16 v[48:51], v[156:159], v[222:225], v[48:51]
	v_mfma_f32_16x16x32_bf16 v[36:39], v[148:151], v[230:233], v[36:39]
	v_mfma_f32_16x16x32_bf16 v[32:35], v[156:159], v[230:233], v[32:35]
	v_mfma_f32_16x16x32_bf16 v[20:23], v[148:151], v[238:241], v[20:23]
	v_mfma_f32_16x16x32_bf16 v[16:19], v[156:159], v[238:241], v[16:19]
	v_mfma_f32_16x16x32_bf16 v[76:79], v[186:189], v[210:213], v[76:79]
	v_mfma_f32_16x16x32_bf16 v[72:75], v[202:205], v[210:213], v[72:75]
	v_mfma_f32_16x16x32_bf16 v[60:63], v[186:189], v[218:221], v[60:63]
	v_mfma_f32_16x16x32_bf16 v[56:59], v[202:205], v[218:221], v[56:59]
	v_mfma_f32_16x16x32_bf16 v[44:47], v[186:189], v[226:229], v[44:47]
	v_mfma_f32_16x16x32_bf16 v[40:43], v[202:205], v[226:229], v[40:43]
	v_mfma_f32_16x16x32_bf16 v[24:27], v[186:189], v[234:237], v[24:27]
	v_mfma_f32_16x16x32_bf16 v[28:31], v[202:205], v[234:237], v[28:31]
	v_mfma_f32_16x16x32_bf16 v[76:79], v[198:201], v[214:217], v[76:79]
	v_mfma_f32_16x16x32_bf16 v[72:75], v[206:209], v[214:217], v[72:75]
	v_mfma_f32_16x16x32_bf16 v[60:63], v[198:201], v[222:225], v[60:63]
	v_mfma_f32_16x16x32_bf16 v[56:59], v[206:209], v[222:225], v[56:59]
	v_mfma_f32_16x16x32_bf16 v[44:47], v[198:201], v[230:233], v[44:47]
	v_mfma_f32_16x16x32_bf16 v[40:43], v[206:209], v[230:233], v[40:43]
	v_mfma_f32_16x16x32_bf16 v[24:27], v[198:201], v[238:241], v[24:27]
	v_mfma_f32_16x16x32_bf16 v[28:31], v[206:209], v[238:241], v[28:31]
	s_barrier
	s_add_i32 s82, 0, 0x18000
	s_add_i32 s83, 0, 0x1c000
	v_add_u32_e32 v156, s82, v195
	v_add_u32_e32 v183, s83, v195
	ds_read_b128 v[144:147], v156
	ds_read_b128 v[148:151], v156 offset:1024
	ds_read_b128 v[152:155], v156 offset:2048
	ds_read_b128 v[156:159], v156 offset:3072
	ds_read_b128 v[186:189], v183
	ds_read_b128 v[198:201], v183 offset:1024
	ds_read_b128 v[202:205], v183 offset:2048
	ds_read_b128 v[206:209], v183 offset:3072
	s_add_u32 s76, s76, 0x40000
	s_addc_u32 s77, s77, 0
	s_mov_b32 m0, s65
	ds_read_b128 v[210:213], v197 offset:32768
	ds_read_b128 v[214:217], v197 offset:33792
	ds_read_b128 v[218:221], v197 offset:34816
	ds_read_b128 v[222:225], v197 offset:35840
	ds_read_b128 v[226:229], v197 offset:36864
	ds_read_b128 v[230:233], v197 offset:37888
	ds_read_b128 v[234:237], v197 offset:38912
	ds_read_b128 v[238:241], v197 offset:39936
	global_load_lds_dwordx4 v172, s[76:77]
	s_mov_b32 m0, s66
	s_nop 0
	global_load_lds_dwordx4 v168, s[76:77]
	s_lshl_b32 s100, s100, 1
	s_and_b32 s100, s100, 6
	s_cmp_eq_u32 s101, 0
	s_cbranch_scc1 .Lpka_nc
	s_cmp_lt_i32 s81, 2
	s_cbranch_scc1 .Lpka_nc
	s_or_b32 s100, s100, 1
	s_cmp_eq_u32 s101, 8
	s_cbranch_scc1 .Lpka_s0c
	s_cmp_eq_u32 s101, 7
	s_cbranch_scc1 .Lpka_s1c
	s_cmp_eq_u32 s101, 6
	s_cbranch_scc1 .Lpka_s2c
	s_cmp_eq_u32 s101, 5
	s_cbranch_scc1 .Lpka_s3c
	s_cmp_eq_u32 s101, 4
	s_cbranch_scc1 .Lpka_s4c
	s_cmp_eq_u32 s101, 3
	s_cbranch_scc1 .Lpka_s5c
	s_cmp_eq_u32 s101, 2
	s_cbranch_scc1 .Lpka_s6c
	global_store_dwordx4 v[254:255], v[12:15], off offset:64
	s_branch .Lpka_ic

; #define PG8_STAGE(bufoff, gbase, voff) do { _Pragma("unroll") for (int _i = 0; _i < 2; ++_i) \
;         __builtin_amdgcn_global_load_lds((const unsigned*)((const char*)(gbase) + (voff)[_i]), (PG8_LAS unsigned*)(lds + (bufoff) + ldsw + _i * 8192), 16, 0, 0); } while (0)
; #define PG8_LDA(dst, b, h) do { _Pragma("unroll") for (int m = 0; m < 4; ++m) _Pragma("unroll") for (int k = 0; k < 2; ++k) dst[m][k] = *(const PG8_LAS bf16x8*)(lds + PG8_SA(b, h) + aoff + m * 2048 + k * 1024); } while (0)
; #define PG8_WAIT_V(n) asm volatile("s_waitcnt vmcnt(" #n ")" ::: "memory")
; #define PG8_WAIT_L(n) asm volatile("s_waitcnt lgkmcnt(" #n ")" ::: "memory")
; #define PG8_BAR __builtin_amdgcn_s_barrier()
; #define PG8_SCHED __builtin_amdgcn_sched_barrier(0)
;     ...
;             PG8_WAIT_V(8); PG8_WAIT_L(0); PG8_BAR; PG8_MMA(0, 0, At, B0); PG8_MMA(0, 1, At, B1); PG8_BAR; PG8_SCHED;
;             PG8_LDA(At, 1, 1); PG8_STAGE(PG8_SB(1, 0), b3, voffB); PG8_STAGE(PG8_SB(1, 1), b3 + hstepB, voffB); PG8_STAGE(PG8_SA(1, 0), a3, voffA);
;             PG8_WAIT_V(8); PG8_WAIT_L(0); PG8_BAR; PG8_MMA(1, 0, At, B0); PG8_MMA(1, 1, At, B1); PG8_BAR; PG8_SCHED;
.Lpka_dc:
	s_barrier
	v_mfma_f32_16x16x32_bf16 v[132:135], v[144:147], v[210:213], v[132:135]
	v_mfma_f32_16x16x32_bf16 v[128:131], v[152:155], v[210:213], v[128:131]
	v_mfma_f32_16x16x32_bf16 v[116:119], v[144:147], v[218:221], v[116:119]
	v_mfma_f32_16x16x32_bf16 v[112:115], v[152:155], v[218:221], v[112:115]
	v_mfma_f32_16x16x32_bf16 v[100:103], v[144:147], v[226:229], v[100:103]
	v_mfma_f32_16x16x32_bf16 v[96:99], v[152:155], v[226:229], v[96:99]
	v_mfma_f32_16x16x32_bf16 v[84:87], v[144:147], v[234:237], v[84:87]
	v_mfma_f32_16x16x32_bf16 v[80:83], v[152:155], v[234:237], v[80:83]
	v_mfma_f32_16x16x32_bf16 v[132:135], v[148:151], v[214:217], v[132:135]
	v_mfma_f32_16x16x32_bf16 v[128:131], v[156:159], v[214:217], v[128:131]
	v_mfma_f32_16x16x32_bf16 v[116:119], v[148:151], v[222:225], v[116:119]
	v_mfma_f32_16x16x32_bf16 v[112:115], v[156:159], v[222:225], v[112:115]
	v_mfma_f32_16x16x32_bf16 v[100:103], v[148:151], v[230:233], v[100:103]
	v_mfma_f32_16x16x32_bf16 v[96:99], v[156:159], v[230:233], v[96:99]
	v_mfma_f32_16x16x32_bf16 v[84:87], v[148:151], v[238:241], v[84:87]
	v_mfma_f32_16x16x32_bf16 v[80:83], v[156:159], v[238:241], v[80:83]
	v_mfma_f32_16x16x32_bf16 v[140:143], v[186:189], v[210:213], v[140:143]
	v_mfma_f32_16x16x32_bf16 v[136:139], v[202:205], v[210:213], v[136:139]
	v_mfma_f32_16x16x32_bf16 v[124:127], v[186:189], v[218:221], v[124:127]
	v_mfma_f32_16x16x32_bf16 v[120:123], v[202:205], v[218:221], v[120:123]
	v_mfma_f32_16x16x32_bf16 v[108:111], v[186:189], v[226:229], v[108:111]
	v_mfma_f32_16x16x32_bf16 v[104:107], v[202:205], v[226:229], v[104:107]
	v_mfma_f32_16x16x32_bf16 v[92:95], v[186:189], v[234:237], v[92:95]
	v_mfma_f32_16x16x32_bf16 v[88:91], v[202:205], v[234:237], v[88:91]
	v_mfma_f32_16x16x32_bf16 v[140:143], v[198:201], v[214:217], v[140:143]
	v_mfma_f32_16x16x32_bf16 v[136:139], v[206:209], v[214:217], v[136:139]
	v_mfma_f32_16x16x32_bf16 v[124:127], v[198:201], v[222:225], v[124:127]
	v_mfma_f32_16x16x32_bf16 v[120:123], v[206:209], v[222:225], v[120:123]
	v_mfma_f32_16x16x32_bf16 v[108:111], v[198:201], v[230:233], v[108:111]
	v_mfma_f32_16x16x32_bf16 v[104:107], v[206:209], v[230:233], v[104:107]
	v_mfma_f32_16x16x32_bf16 v[92:95], v[198:201], v[238:241], v[92:95]
	v_mfma_f32_16x16x32_bf16 v[88:91], v[206:209], v[238:241], v[88:91]
	s_barrier
	s_add_i32 m0, s82, s15
	s_add_u32 vcc_lo, s72, 0x80
	s_addc_u32 vcc_hi, s73, 0
	ds_read_b128 v[210:213], v197 offset:49152
	ds_read_b128 v[214:217], v197 offset:50176
	ds_read_b128 v[218:221], v197 offset:51200
	ds_read_b128 v[222:225], v197 offset:52224
	ds_read_b128 v[226:229], v197 offset:53248
	ds_read_b128 v[230:233], v197 offset:54272
	ds_read_b128 v[234:237], v197 offset:55296
	ds_read_b128 v[238:241], v197 offset:56320
	global_load_lds_dwordx4 v170, vcc
	s_add_i32 m0, m0, 0x2000
	s_nop 0
	global_load_lds_dwordx4 v166, vcc
	s_add_u32 s72, s72, 0x10080
	s_addc_u32 s73, s73, 0
	s_add_i32 m0, s83, s15
	s_nop 0
	global_load_lds_dwordx4 v170, s[72:73]
	s_add_i32 m0, m0, 0x2000
	s_nop 0
	global_load_lds_dwordx4 v166, s[72:73]
	s_add_u32 vcc_lo, s76, 0xfffc0080
	s_addc_u32 vcc_hi, s77, -1
	s_mov_b32 m0, s74
	s_nop 0
	global_load_lds_dwordx4 v172, vcc
	s_mov_b32 m0, s75
	s_nop 0
	global_load_lds_dwordx4 v168, vcc
	s_lshl_b32 s100, s100, 1
	s_and_b32 s100, s100, 6
	s_bcnt1_i32_b32 vcc_lo, s100
	s_cmp_eq_u32 vcc_lo, 0
	s_cbranch_scc1 .Lpka_w8e
	s_cmp_eq_u32 vcc_lo, 1
	s_cbranch_scc1 .Lpka_w9e
	s_waitcnt vmcnt(10) lgkmcnt(0)
	s_branch .Lpka_de

; #define PG8_WAIT_V(n) asm volatile("s_waitcnt vmcnt(" #n ")" ::: "memory")
; #define PG8_WAIT_L(n) asm volatile("s_waitcnt lgkmcnt(" #n ")" ::: "memory")
; #define PG8_BAR __builtin_amdgcn_s_barrier()
; #define PG8_SCHED __builtin_amdgcn_sched_barrier(0)
;     ...
;             PG8_WAIT_V(8); PG8_WAIT_L(0); PG8_BAR; PG8_MMA(1, 0, At, B0); PG8_MMA(1, 1, At, B1); PG8_BAR; PG8_SCHED;
;         }
;         if constexpr (ALIGN_EPI) { if (wr == 0) PG8_BAR; }
.Lpka_de:
	s_barrier
	v_mfma_f32_16x16x32_bf16 v[68:71], v[144:147], v[210:213], v[68:71]
	v_mfma_f32_16x16x32_bf16 v[64:67], v[152:155], v[210:213], v[64:67]
	v_mfma_f32_16x16x32_bf16 v[52:55], v[144:147], v[218:221], v[52:55]
	v_mfma_f32_16x16x32_bf16 v[48:51], v[152:155], v[218:221], v[48:51]
	v_mfma_f32_16x16x32_bf16 v[36:39], v[144:147], v[226:229], v[36:39]
	v_mfma_f32_16x16x32_bf16 v[32:35], v[152:155], v[226:229], v[32:35]
	v_mfma_f32_16x16x32_bf16 v[20:23], v[144:147], v[234:237], v[20:23]
	v_mfma_f32_16x16x32_bf16 v[16:19], v[152:155], v[234:237], v[16:19]
	v_mfma_f32_16x16x32_bf16 v[68:71], v[148:151], v[214:217], v[68:71]
	v_mfma_f32_16x16x32_bf16 v[64:67], v[156:159], v[214:217], v[64:67]
	v_mfma_f32_16x16x32_bf16 v[52:55], v[148:151], v[222:225], v[52:55]
	v_mfma_f32_16x16x32_bf16 v[48:51], v[156:159], v[222:225], v[48:51]
	v_mfma_f32_16x16x32_bf16 v[36:39], v[148:151], v[230:233], v[36:39]
	v_mfma_f32_16x16x32_bf16 v[32:35], v[156:159], v[230:233], v[32:35]
	v_mfma_f32_16x16x32_bf16 v[20:23], v[148:151], v[238:241], v[20:23]
	v_mfma_f32_16x16x32_bf16 v[16:19], v[156:159], v[238:241], v[16:19]
	v_mfma_f32_16x16x32_bf16 v[76:79], v[186:189], v[210:213], v[76:79]
	v_mfma_f32_16x16x32_bf16 v[72:75], v[202:205], v[210:213], v[72:75]
	v_mfma_f32_16x16x32_bf16 v[60:63], v[186:189], v[218:221], v[60:63]
	v_mfma_f32_16x16x32_bf16 v[56:59], v[202:205], v[218:221], v[56:59]
	v_mfma_f32_16x16x32_bf16 v[44:47], v[186:189], v[226:229], v[44:47]
	v_mfma_f32_16x16x32_bf16 v[40:43], v[202:205], v[226:229], v[40:43]
	v_mfma_f32_16x16x32_bf16 v[24:27], v[186:189], v[234:237], v[24:27]
	v_mfma_f32_16x16x32_bf16 v[28:31], v[202:205], v[234:237], v[28:31]
	v_mfma_f32_16x16x32_bf16 v[76:79], v[198:201], v[214:217], v[76:79]
	v_mfma_f32_16x16x32_bf16 v[72:75], v[206:209], v[214:217], v[72:75]
	v_mfma_f32_16x16x32_bf16 v[60:63], v[198:201], v[222:225], v[60:63]
	v_mfma_f32_16x16x32_bf16 v[56:59], v[206:209], v[222:225], v[56:59]
	v_mfma_f32_16x16x32_bf16 v[44:47], v[198:201], v[230:233], v[44:47]
	v_mfma_f32_16x16x32_bf16 v[40:43], v[206:209], v[230:233], v[40:43]
	v_mfma_f32_16x16x32_bf16 v[24:27], v[198:201], v[238:241], v[24:27]
	v_mfma_f32_16x16x32_bf16 v[28:31], v[206:209], v[238:241], v[28:31]
	s_barrier
	s_add_i32 s81, s81, 2
	s_add_u32 s38, s38, 0x100
	s_addc_u32 s39, s39, 0
	s_add_u32 s61, s61, 0x100
	s_addc_u32 s80, s80, 0
	s_cmp_gt_u32 s81, 13
	s_cbranch_scc0 .LBB0_206
	v_mov_b32_e32 v162, 0x500
	v_mov_b32_e32 v163, 0
	v_mov_b32_e32 v164, 0x4ff
	v_mov_b32_e32 v165, 0
	v_mov_b32_e32 v190, 0x358637bd
	v_mov_b32_e32 v191, 1
	v_mov_b32_e32 v192, 0x300
	v_mov_b32_e32 v193, 0x200
	s_and_b64 vcc, exec, s[22:23]
	s_cbranch_vccz .LBB0_209
	s_barrier

; #define PG8_STAGE(bufoff, gbase, voff) do { _Pragma("unroll") for (int _i = 0; _i < 2; ++_i) \
;         __builtin_amdgcn_global_load_lds((const unsigned*)((const char*)(gbase) + (voff)[_i]), (PG8_LAS unsigned*)(lds + (bufoff) + ldsw + _i * 8192), 16, 0, 0); } while (0)
; #define PG8_LDA(dst, b, h) do { _Pragma("unroll") for (int m = 0; m < 4; ++m) _Pragma("unroll") for (int k = 0; k < 2; ++k) dst[m][k] = *(const PG8_LAS bf16x8*)(lds + PG8_SA(b, h) + aoff + m * 2048 + k * 1024); } while (0)
; #define PG8_LDB(dst, b, h) do { _Pragma("unroll") for (int n = 0; n < 2; ++n) _Pragma("unroll") for (int k = 0; k < 2; ++k) dst[n][k] = *(const PG8_LAS bf16x8*)(lds + PG8_SB(b, h) + boff + n * 2048 + k * 1024); } while (0)
; #define PG8_WAIT_V(n) asm volatile("s_waitcnt vmcnt(" #n ")" ::: "memory")
; #define PG8_WAIT_L(n) asm volatile("s_waitcnt lgkmcnt(" #n ")" ::: "memory")
; #define PG8_BAR __builtin_amdgcn_s_barrier()
; #define PG8_SCHED __builtin_amdgcn_sched_barrier(0)
;     ...
;         for (int t = 0; t < nt; t += 2) {
;             const bool last = (t == nt - 2);
;             const char* a1 = cA + (size_t)(t + 1) * kstep;
;             const char* a2 = last ? nA : cA + (size_t)(t + 2) * kstep; const char* b2 = last ? nB : cB + (size_t)(t + 2) * kstep;
;             const char* a3 = a2 + kstep; const char* b3 = b2 + kstep;
;             PG8_LDB(B0, 0, 0); PG8_LDB(B1, 0, 1); PG8_SCHED; PG8_LDA(At, 0, 0); PG8_STAGE(PG8_SA(1, 1), a1 + hstep, voffA);
;             PG8_WAIT_V(8); PG8_WAIT_L(0); PG8_BAR; PG8_MMA(0, 0, At, B0); PG8_MMA(0, 1, At, B1); PG8_BAR; PG8_SCHED;
;             PG8_LDA(At, 0, 1); PG8_STAGE(PG8_SB(0, 0), b2, voffB); PG8_STAGE(PG8_SB(0, 1), b2 + hstepB, voffB); PG8_STAGE(PG8_SA(0, 0), a2, voffA);
.LBB0_434:
	v_add_u32_e32 v140, s49, v199
	s_waitcnt lgkmcnt(0)
	v_add_u32_e32 v156, s50, v199
	ds_read_b128 v[128:131], v140
	ds_read_b128 v[132:135], v140 offset:1024
	ds_read_b128 v[136:139], v140 offset:2048
	ds_read_b128 v[140:143], v140 offset:3072
	ds_read_b128 v[144:147], v156
	ds_read_b128 v[148:151], v156 offset:1024
	ds_read_b128 v[152:155], v156 offset:2048
	ds_read_b128 v[156:159], v156 offset:3072
	s_add_u32 s22, s24, 0xfffc0080
	s_addc_u32 s23, s25, -1
	s_cmp_eq_u32 s54, 12
	s_cselect_b32 s27, s2, s23
	s_cselect_b32 s26, s15, s22
	s_cselect_b32 s23, s13, s53
	s_cselect_b32 s22, s21, s52
	v_lshl_add_u64 v[196:197], s[24:25], 0, v[184:185]
	s_add_i32 m0, s29, 0xc000
	ds_read_b128 v[160:163], v201
	ds_read_b128 v[164:167], v201 offset:1024
	ds_read_b128 v[168:171], v201 offset:2048
	ds_read_b128 v[172:175], v201 offset:3072
	ds_read_b128 v[192:195], v201 offset:4096
	ds_read_b128 v[202:205], v201 offset:5120
	ds_read_b128 v[206:209], v201 offset:6144
	ds_read_b128 v[210:213], v201 offset:7168
	global_load_lds_dwordx4 v[196:197], off
	s_add_i32 m0, s29, 0xe000
	v_lshl_add_u64 v[196:197], s[24:25], 0, v[186:187]
	global_load_lds_dwordx4 v[196:197], off
	s_waitcnt vmcnt(8) lgkmcnt(0)
	s_barrier
	v_mfma_f32_16x16x32_bf16 v[112:115], v[128:131], v[160:163], v[112:115]
	v_mfma_f32_16x16x32_bf16 v[116:119], v[136:139], v[160:163], v[116:119]
	v_mfma_f32_16x16x32_bf16 v[108:111], v[128:131], v[168:171], v[108:111]
	v_mfma_f32_16x16x32_bf16 v[104:107], v[136:139], v[168:171], v[104:107]
	v_mfma_f32_16x16x32_bf16 v[92:95], v[128:131], v[192:195], v[92:95]
	v_mfma_f32_16x16x32_bf16 v[88:91], v[136:139], v[192:195], v[88:91]
	v_mfma_f32_16x16x32_bf16 v[76:79], v[128:131], v[206:209], v[76:79]
	v_mfma_f32_16x16x32_bf16 v[72:75], v[136:139], v[206:209], v[72:75]
	v_mfma_f32_16x16x32_bf16 v[112:115], v[132:135], v[164:167], v[112:115]
	v_mfma_f32_16x16x32_bf16 v[116:119], v[140:143], v[164:167], v[116:119]
	v_mfma_f32_16x16x32_bf16 v[108:111], v[132:135], v[172:175], v[108:111]
	v_mfma_f32_16x16x32_bf16 v[104:107], v[140:143], v[172:175], v[104:107]
	v_mfma_f32_16x16x32_bf16 v[92:95], v[132:135], v[202:205], v[92:95]
	v_mfma_f32_16x16x32_bf16 v[88:91], v[140:143], v[202:205], v[88:91]
	v_mfma_f32_16x16x32_bf16 v[76:79], v[132:135], v[210:213], v[76:79]
	v_mfma_f32_16x16x32_bf16 v[72:75], v[140:143], v[210:213], v[72:75]
	v_mfma_f32_16x16x32_bf16 v[120:123], v[144:147], v[160:163], v[120:123]
	v_mfma_f32_16x16x32_bf16 v[124:127], v[152:155], v[160:163], v[124:127]
	v_mfma_f32_16x16x32_bf16 v[100:103], v[144:147], v[168:171], v[100:103]
	v_mfma_f32_16x16x32_bf16 v[96:99], v[152:155], v[168:171], v[96:99]
	v_mfma_f32_16x16x32_bf16 v[84:87], v[144:147], v[192:195], v[84:87]
	v_mfma_f32_16x16x32_bf16 v[80:83], v[152:155], v[192:195], v[80:83]
	v_mfma_f32_16x16x32_bf16 v[68:71], v[144:147], v[206:209], v[68:71]
	v_mfma_f32_16x16x32_bf16 v[64:67], v[152:155], v[206:209], v[64:67]
	v_mfma_f32_16x16x32_bf16 v[120:123], v[148:151], v[164:167], v[120:123]
	v_mfma_f32_16x16x32_bf16 v[124:127], v[156:159], v[164:167], v[124:127]
	v_mfma_f32_16x16x32_bf16 v[100:103], v[148:151], v[172:175], v[100:103]
	v_mfma_f32_16x16x32_bf16 v[96:99], v[156:159], v[172:175], v[96:99]
	v_mfma_f32_16x16x32_bf16 v[84:87], v[148:151], v[202:205], v[84:87]
	v_mfma_f32_16x16x32_bf16 v[80:83], v[156:159], v[202:205], v[80:83]
	v_mfma_f32_16x16x32_bf16 v[68:71], v[148:151], v[210:213], v[68:71]
	v_mfma_f32_16x16x32_bf16 v[64:67], v[156:159], v[210:213], v[64:67]
	s_barrier
	s_add_i32 s55, s49, s28
	v_lshl_add_u64 v[196:197], s[22:23], 0, v[178:179]
	s_mov_b32 m0, s55
	ds_read_b128 v[160:163], v201 offset:16384
	ds_read_b128 v[164:167], v201 offset:17408
	ds_read_b128 v[168:171], v201 offset:18432
	ds_read_b128 v[172:175], v201 offset:19456
	ds_read_b128 v[192:195], v201 offset:20480
	ds_read_b128 v[202:205], v201 offset:21504
	ds_read_b128 v[206:209], v201 offset:22528
	ds_read_b128 v[210:213], v201 offset:23552
	global_load_lds_dwordx4 v[196:197], off
	s_add_i32 m0, s55, 0x2000
	s_add_u32 s56, s22, 0x40000
	v_lshl_add_u64 v[214:215], s[22:23], 0, v[176:177]
	s_addc_u32 s57, s23, 0
	s_add_i32 s55, s50, s28
	global_load_lds_dwordx4 v[214:215], off
	v_lshl_add_u64 v[216:217], s[56:57], 0, v[178:179]
	s_mov_b32 m0, s55
	v_lshl_add_u64 v[218:219], s[26:27], 0, v[176:177]
	global_load_lds_dwordx4 v[216:217], off
	s_add_i32 m0, s55, 0x2000
	v_lshl_add_u64 v[216:217], s[56:57], 0, v[176:177]
	global_load_lds_dwordx4 v[216:217], off
	s_mov_b32 m0, s29
	v_lshl_add_u64 v[216:217], s[26:27], 0, v[178:179]
	global_load_lds_dwordx4 v[216:217], off
	s_mov_b32 m0, s33
	s_nop 0
	global_load_lds_dwordx4 v[218:219], off
	s_waitcnt vmcnt(8) lgkmcnt(0)
	s_barrier
; #define PG8_STAGE(bufoff, gbase, voff) do { _Pragma("unroll") for (int _i = 0; _i < 2; ++_i) \
;         __builtin_amdgcn_global_load_lds((const unsigned*)((const char*)(gbase) + (voff)[_i]), (PG8_LAS unsigned*)(lds + (bufoff) + ldsw + _i * 8192), 16, 0, 0); } while (0)
; #define PG8_LDA(dst, b, h) do { _Pragma("unroll") for (int m = 0; m < 4; ++m) _Pragma("unroll") for (int k = 0; k < 2; ++k) dst[m][k] = *(const PG8_LAS bf16x8*)(lds + PG8_SA(b, h) + aoff + m * 2048 + k * 1024); } while (0)
; #define PG8_LDB(dst, b, h) do { _Pragma("unroll") for (int n = 0; n < 2; ++n) _Pragma("unroll") for (int k = 0; k < 2; ++k) dst[n][k] = *(const PG8_LAS bf16x8*)(lds + PG8_SB(b, h) + boff + n * 2048 + k * 1024); } while (0)
; #define PG8_WAIT_V(n) asm volatile("s_waitcnt vmcnt(" #n ")" ::: "memory")
; #define PG8_WAIT_L(n) asm volatile("s_waitcnt lgkmcnt(" #n ")" ::: "memory")
; #define PG8_BAR __builtin_amdgcn_s_barrier()
; #define PG8_SCHED __builtin_amdgcn_sched_barrier(0)
;     ...
;             PG8_WAIT_V(8); PG8_WAIT_L(0); PG8_BAR; PG8_MMA(1, 0, At, B0); PG8_MMA(1, 1, At, B1); PG8_BAR; PG8_SCHED;
;             PG8_LDB(B0, 1, 0); PG8_LDB(B1, 1, 1); PG8_SCHED; PG8_LDA(At, 1, 0); PG8_STAGE(PG8_SA(0, 1), a2 + hstep, voffA);
;             PG8_WAIT_V(8); PG8_WAIT_L(0); PG8_BAR; PG8_MMA(0, 0, At, B0); PG8_MMA(0, 1, At, B1); PG8_BAR; PG8_SCHED;
	v_mfma_f32_16x16x32_bf16 v[60:63], v[128:131], v[160:163], v[60:63]
	v_mfma_f32_16x16x32_bf16 v[52:55], v[136:139], v[160:163], v[52:55]
	v_mfma_f32_16x16x32_bf16 v[44:47], v[128:131], v[168:171], v[44:47]
	v_mfma_f32_16x16x32_bf16 v[36:39], v[136:139], v[168:171], v[36:39]
	v_mfma_f32_16x16x32_bf16 v[28:31], v[128:131], v[192:195], v[28:31]
	v_mfma_f32_16x16x32_bf16 v[20:23], v[136:139], v[192:195], v[20:23]
	v_mfma_f32_16x16x32_bf16 v[8:11], v[128:131], v[206:209], v[8:11]
	v_mfma_f32_16x16x32_bf16 v[0:3], v[136:139], v[206:209], v[0:3]
	v_mfma_f32_16x16x32_bf16 v[60:63], v[132:135], v[164:167], v[60:63]
	v_mfma_f32_16x16x32_bf16 v[52:55], v[140:143], v[164:167], v[52:55]
	v_mfma_f32_16x16x32_bf16 v[44:47], v[132:135], v[172:175], v[44:47]
	v_mfma_f32_16x16x32_bf16 v[36:39], v[140:143], v[172:175], v[36:39]
	v_mfma_f32_16x16x32_bf16 v[28:31], v[132:135], v[202:205], v[28:31]
	v_mfma_f32_16x16x32_bf16 v[20:23], v[140:143], v[202:205], v[20:23]
	v_mfma_f32_16x16x32_bf16 v[8:11], v[132:135], v[210:213], v[8:11]
	v_mfma_f32_16x16x32_bf16 v[0:3], v[140:143], v[210:213], v[0:3]
	v_mfma_f32_16x16x32_bf16 v[56:59], v[144:147], v[160:163], v[56:59]
	v_mfma_f32_16x16x32_bf16 v[48:51], v[152:155], v[160:163], v[48:51]
	v_mfma_f32_16x16x32_bf16 v[40:43], v[144:147], v[168:171], v[40:43]
	v_mfma_f32_16x16x32_bf16 v[32:35], v[152:155], v[168:171], v[32:35]
	v_mfma_f32_16x16x32_bf16 v[24:27], v[144:147], v[192:195], v[24:27]
	v_mfma_f32_16x16x32_bf16 v[16:19], v[152:155], v[192:195], v[16:19]
	v_mfma_f32_16x16x32_bf16 v[4:7], v[144:147], v[206:209], v[4:7]
	v_mfma_f32_16x16x32_bf16 v[12:15], v[152:155], v[206:209], v[12:15]
	v_mfma_f32_16x16x32_bf16 v[56:59], v[148:151], v[164:167], v[56:59]
	v_mfma_f32_16x16x32_bf16 v[48:51], v[156:159], v[164:167], v[48:51]
	v_mfma_f32_16x16x32_bf16 v[40:43], v[148:151], v[172:175], v[40:43]
	v_mfma_f32_16x16x32_bf16 v[32:35], v[156:159], v[172:175], v[32:35]
	v_mfma_f32_16x16x32_bf16 v[24:27], v[148:151], v[202:205], v[24:27]
	v_mfma_f32_16x16x32_bf16 v[16:19], v[156:159], v[202:205], v[16:19]
	v_mfma_f32_16x16x32_bf16 v[4:7], v[148:151], v[210:213], v[4:7]
	v_mfma_f32_16x16x32_bf16 v[12:15], v[156:159], v[210:213], v[12:15]
	s_barrier
	s_add_i32 s55, 0, 0x18000
	s_add_i32 s56, 0, 0x1c000
	v_add_u32_e32 v140, s55, v199
	v_add_u32_e32 v156, s56, v199
	ds_read_b128 v[128:131], v140
	ds_read_b128 v[132:135], v140 offset:1024
	ds_read_b128 v[136:139], v140 offset:2048
	ds_read_b128 v[140:143], v140 offset:3072
	ds_read_b128 v[144:147], v156
	ds_read_b128 v[148:151], v156 offset:1024
	ds_read_b128 v[152:155], v156 offset:2048
	ds_read_b128 v[156:159], v156 offset:3072
	s_add_u32 s26, s26, 0x40000
	s_addc_u32 s27, s27, 0
	s_mov_b32 m0, s36
	v_lshl_add_u64 v[220:221], s[26:27], 0, v[178:179]
	ds_read_b128 v[160:163], v201 offset:32768
	ds_read_b128 v[164:167], v201 offset:33792
	ds_read_b128 v[168:171], v201 offset:34816
	ds_read_b128 v[172:175], v201 offset:35840
	ds_read_b128 v[192:195], v201 offset:36864
	ds_read_b128 v[202:205], v201 offset:37888
	ds_read_b128 v[206:209], v201 offset:38912
	ds_read_b128 v[210:213], v201 offset:39936
	global_load_lds_dwordx4 v[220:221], off
	s_mov_b32 m0, s37
	v_lshl_add_u64 v[220:221], s[26:27], 0, v[176:177]
	global_load_lds_dwordx4 v[220:221], off
	s_waitcnt vmcnt(8) lgkmcnt(0)
	s_barrier
	v_mfma_f32_16x16x32_bf16 v[112:115], v[128:131], v[160:163], v[112:115]
	v_mfma_f32_16x16x32_bf16 v[116:119], v[136:139], v[160:163], v[116:119]
	v_mfma_f32_16x16x32_bf16 v[108:111], v[128:131], v[168:171], v[108:111]
	v_mfma_f32_16x16x32_bf16 v[104:107], v[136:139], v[168:171], v[104:107]
	v_mfma_f32_16x16x32_bf16 v[92:95], v[128:131], v[192:195], v[92:95]
	v_mfma_f32_16x16x32_bf16 v[88:91], v[136:139], v[192:195], v[88:91]
	v_mfma_f32_16x16x32_bf16 v[76:79], v[128:131], v[206:209], v[76:79]
	v_mfma_f32_16x16x32_bf16 v[72:75], v[136:139], v[206:209], v[72:75]
	v_mfma_f32_16x16x32_bf16 v[112:115], v[132:135], v[164:167], v[112:115]
	v_mfma_f32_16x16x32_bf16 v[116:119], v[140:143], v[164:167], v[116:119]
	v_mfma_f32_16x16x32_bf16 v[108:111], v[132:135], v[172:175], v[108:111]
	v_mfma_f32_16x16x32_bf16 v[104:107], v[140:143], v[172:175], v[104:107]
	v_mfma_f32_16x16x32_bf16 v[92:95], v[132:135], v[202:205], v[92:95]
	v_mfma_f32_16x16x32_bf16 v[88:91], v[140:143], v[202:205], v[88:91]
	v_mfma_f32_16x16x32_bf16 v[76:79], v[132:135], v[210:213], v[76:79]
	v_mfma_f32_16x16x32_bf16 v[72:75], v[140:143], v[210:213], v[72:75]
	v_mfma_f32_16x16x32_bf16 v[120:123], v[144:147], v[160:163], v[120:123]
	v_mfma_f32_16x16x32_bf16 v[124:127], v[152:155], v[160:163], v[124:127]
	v_mfma_f32_16x16x32_bf16 v[100:103], v[144:147], v[168:171], v[100:103]
	v_mfma_f32_16x16x32_bf16 v[96:99], v[152:155], v[168:171], v[96:99]
	v_mfma_f32_16x16x32_bf16 v[84:87], v[144:147], v[192:195], v[84:87]
	v_mfma_f32_16x16x32_bf16 v[80:83], v[152:155], v[192:195], v[80:83]
	v_mfma_f32_16x16x32_bf16 v[68:71], v[144:147], v[206:209], v[68:71]
	v_mfma_f32_16x16x32_bf16 v[64:67], v[152:155], v[206:209], v[64:67]
	v_mfma_f32_16x16x32_bf16 v[120:123], v[148:151], v[164:167], v[120:123]
	v_mfma_f32_16x16x32_bf16 v[124:127], v[156:159], v[164:167], v[124:127]
	v_mfma_f32_16x16x32_bf16 v[100:103], v[148:151], v[172:175], v[100:103]
	v_mfma_f32_16x16x32_bf16 v[96:99], v[156:159], v[172:175], v[96:99]
	v_mfma_f32_16x16x32_bf16 v[84:87], v[148:151], v[202:205], v[84:87]
	v_mfma_f32_16x16x32_bf16 v[80:83], v[156:159], v[202:205], v[80:83]
	v_mfma_f32_16x16x32_bf16 v[68:71], v[148:151], v[210:213], v[68:71]
	v_mfma_f32_16x16x32_bf16 v[64:67], v[156:159], v[210:213], v[64:67]
	s_barrier
; #define PG8_STAGE(bufoff, gbase, voff) do { _Pragma("unroll") for (int _i = 0; _i < 2; ++_i) \
;         __builtin_amdgcn_global_load_lds((const unsigned*)((const char*)(gbase) + (voff)[_i]), (PG8_LAS unsigned*)(lds + (bufoff) + ldsw + _i * 8192), 16, 0, 0); } while (0)
; #define PG8_LDA(dst, b, h) do { _Pragma("unroll") for (int m = 0; m < 4; ++m) _Pragma("unroll") for (int k = 0; k < 2; ++k) dst[m][k] = *(const PG8_LAS bf16x8*)(lds + PG8_SA(b, h) + aoff + m * 2048 + k * 1024); } while (0)
; #define PG8_WAIT_V(n) asm volatile("s_waitcnt vmcnt(" #n ")" ::: "memory")
; #define PG8_WAIT_L(n) asm volatile("s_waitcnt lgkmcnt(" #n ")" ::: "memory")
; #define PG8_BAR __builtin_amdgcn_s_barrier()
; #define PG8_SCHED __builtin_amdgcn_sched_barrier(0)
;     ...
;             PG8_LDA(At, 1, 1); PG8_STAGE(PG8_SB(1, 0), b3, voffB); PG8_STAGE(PG8_SB(1, 1), b3 + hstepB, voffB); PG8_STAGE(PG8_SA(1, 0), a3, voffA);
;             PG8_WAIT_V(8); PG8_WAIT_L(0); PG8_BAR; PG8_MMA(1, 0, At, B0); PG8_MMA(1, 1, At, B1); PG8_BAR; PG8_SCHED;
;         }
	s_add_i32 s26, s55, s28
	v_lshl_add_u64 v[196:197], v[196:197], 0, s[8:9]
	s_mov_b32 m0, s26
	ds_read_b128 v[160:163], v201 offset:49152
	ds_read_b128 v[164:167], v201 offset:50176
	ds_read_b128 v[168:171], v201 offset:51200
	ds_read_b128 v[172:175], v201 offset:52224
	ds_read_b128 v[192:195], v201 offset:53248
	ds_read_b128 v[202:205], v201 offset:54272
	ds_read_b128 v[206:209], v201 offset:55296
	ds_read_b128 v[210:213], v201 offset:56320
	global_load_lds_dwordx4 v[196:197], off
	s_add_i32 m0, s26, 0x2000
	s_add_u32 s22, s22, 0x40080
	v_lshl_add_u64 v[196:197], v[214:215], 0, s[8:9]
	s_addc_u32 s23, s23, 0
	s_add_i32 s26, s56, s28
	global_load_lds_dwordx4 v[196:197], off
	s_mov_b32 m0, s26
	v_lshl_add_u64 v[196:197], s[22:23], 0, v[178:179]
	global_load_lds_dwordx4 v[196:197], off
	s_add_i32 m0, s26, 0x2000
	v_lshl_add_u64 v[196:197], s[22:23], 0, v[176:177]
	global_load_lds_dwordx4 v[196:197], off
	s_mov_b32 m0, s41
	v_lshl_add_u64 v[196:197], v[216:217], 0, s[8:9]
	global_load_lds_dwordx4 v[196:197], off
	s_mov_b32 m0, s42
	v_lshl_add_u64 v[196:197], v[218:219], 0, s[8:9]
	global_load_lds_dwordx4 v[196:197], off
	s_waitcnt vmcnt(8) lgkmcnt(0)
	s_barrier
	v_mfma_f32_16x16x32_bf16 v[60:63], v[128:131], v[160:163], v[60:63]
	v_mfma_f32_16x16x32_bf16 v[52:55], v[136:139], v[160:163], v[52:55]
	v_mfma_f32_16x16x32_bf16 v[44:47], v[128:131], v[168:171], v[44:47]
	v_mfma_f32_16x16x32_bf16 v[36:39], v[136:139], v[168:171], v[36:39]
	v_mfma_f32_16x16x32_bf16 v[28:31], v[128:131], v[192:195], v[28:31]
	v_mfma_f32_16x16x32_bf16 v[20:23], v[136:139], v[192:195], v[20:23]
	v_mfma_f32_16x16x32_bf16 v[8:11], v[128:131], v[206:209], v[8:11]
	v_mfma_f32_16x16x32_bf16 v[0:3], v[136:139], v[206:209], v[0:3]
	v_mfma_f32_16x16x32_bf16 v[60:63], v[132:135], v[164:167], v[60:63]
	v_mfma_f32_16x16x32_bf16 v[52:55], v[140:143], v[164:167], v[52:55]
	v_mfma_f32_16x16x32_bf16 v[44:47], v[132:135], v[172:175], v[44:47]
	v_mfma_f32_16x16x32_bf16 v[36:39], v[140:143], v[172:175], v[36:39]
	v_mfma_f32_16x16x32_bf16 v[28:31], v[132:135], v[202:205], v[28:31]
	v_mfma_f32_16x16x32_bf16 v[20:23], v[140:143], v[202:205], v[20:23]
	v_mfma_f32_16x16x32_bf16 v[8:11], v[132:135], v[210:213], v[8:11]
	v_mfma_f32_16x16x32_bf16 v[0:3], v[140:143], v[210:213], v[0:3]
	v_mfma_f32_16x16x32_bf16 v[56:59], v[144:147], v[160:163], v[56:59]
	v_mfma_f32_16x16x32_bf16 v[48:51], v[152:155], v[160:163], v[48:51]
	v_mfma_f32_16x16x32_bf16 v[40:43], v[144:147], v[168:171], v[40:43]
	v_mfma_f32_16x16x32_bf16 v[32:35], v[152:155], v[168:171], v[32:35]
	v_mfma_f32_16x16x32_bf16 v[24:27], v[144:147], v[192:195], v[24:27]
	v_mfma_f32_16x16x32_bf16 v[16:19], v[152:155], v[192:195], v[16:19]
	v_mfma_f32_16x16x32_bf16 v[4:7], v[144:147], v[206:209], v[4:7]
	v_mfma_f32_16x16x32_bf16 v[12:15], v[152:155], v[206:209], v[12:15]
	v_mfma_f32_16x16x32_bf16 v[56:59], v[148:151], v[164:167], v[56:59]
	v_mfma_f32_16x16x32_bf16 v[48:51], v[156:159], v[164:167], v[48:51]
	v_mfma_f32_16x16x32_bf16 v[40:43], v[148:151], v[172:175], v[40:43]
	v_mfma_f32_16x16x32_bf16 v[32:35], v[156:159], v[172:175], v[32:35]
	v_mfma_f32_16x16x32_bf16 v[24:27], v[148:151], v[202:205], v[24:27]
	v_mfma_f32_16x16x32_bf16 v[16:19], v[156:159], v[202:205], v[16:19]
	v_mfma_f32_16x16x32_bf16 v[4:7], v[148:151], v[210:213], v[4:7]
	v_mfma_f32_16x16x32_bf16 v[12:15], v[156:159], v[210:213], v[12:15]
	s_barrier
	s_add_i32 s54, s54, 2
	s_add_u32 s24, s24, 0x100
	s_addc_u32 s25, s25, 0
	s_add_u32 s52, s52, 0x100
	s_addc_u32 s53, s53, 0
	s_cmp_gt_u32 s54, 13
	s_cbranch_scc0 .LBB0_434
	s_and_b64 vcc, exec, s[10:11]
	s_cbranch_vccz .LBB0_437
	s_barrier

; #define PG8_STAGE(bufoff, gbase, voff) do { _Pragma("unroll") for (int _i = 0; _i < 2; ++_i) \
;         __builtin_amdgcn_global_load_lds((const unsigned*)((const char*)(gbase) + (voff)[_i]), (PG8_LAS unsigned*)(lds + (bufoff) + ldsw + _i * 8192), 16, 0, 0); } while (0)
; #define PG8_LDA(dst, b, h) do { _Pragma("unroll") for (int m = 0; m < 4; ++m) _Pragma("unroll") for (int k = 0; k < 2; ++k) dst[m][k] = *(const PG8_LAS bf16x8*)(lds + PG8_SA(b, h) + aoff + m * 2048 + k * 1024); } while (0)
; #define PG8_LDB(dst, b, h) do { _Pragma("unroll") for (int n = 0; n < 2; ++n) _Pragma("unroll") for (int k = 0; k < 2; ++k) dst[n][k] = *(const PG8_LAS bf16x8*)(lds + PG8_SB(b, h) + boff + n * 2048 + k * 1024); } while (0)
; #define PG8_WAIT_V(n) asm volatile("s_waitcnt vmcnt(" #n ")" ::: "memory")
; #define PG8_WAIT_L(n) asm volatile("s_waitcnt lgkmcnt(" #n ")" ::: "memory")
; #define PG8_BAR __builtin_amdgcn_s_barrier()
; #define PG8_SCHED __builtin_amdgcn_sched_barrier(0)
;     ...
;             PG8_LDB(B0, 0, 0); PG8_LDB(B1, 0, 1); PG8_SCHED; PG8_LDA(At, 0, 0); PG8_STAGE(PG8_SA(1, 1), a1 + hstep, voffA);
;             PG8_WAIT_V(8); PG8_WAIT_L(0); PG8_BAR; PG8_MMA(0, 0, At, B0); PG8_MMA(0, 1, At, B1); PG8_BAR; PG8_SCHED;
.Lpkb_w9a:
	s_bitset1_b32 s101, 16
	s_waitcnt vmcnt(9) lgkmcnt(0)
	s_branch .Lpkb_da

; #define PG8_STAGE(bufoff, gbase, voff) do { _Pragma("unroll") for (int _i = 0; _i < 2; ++_i) \
;         __builtin_amdgcn_global_load_lds((const unsigned*)((const char*)(gbase) + (voff)[_i]), (PG8_LAS unsigned*)(lds + (bufoff) + ldsw + _i * 8192), 16, 0, 0); } while (0)
; #define PG8_LDA(dst, b, h) do { _Pragma("unroll") for (int m = 0; m < 4; ++m) _Pragma("unroll") for (int k = 0; k < 2; ++k) dst[m][k] = *(const PG8_LAS bf16x8*)(lds + PG8_SA(b, h) + aoff + m * 2048 + k * 1024); } while (0)
; #define PG8_WAIT_V(n) asm volatile("s_waitcnt vmcnt(" #n ")" ::: "memory")
; #define PG8_WAIT_L(n) asm volatile("s_waitcnt lgkmcnt(" #n ")" ::: "memory")
; #define PG8_BAR __builtin_amdgcn_s_barrier()
; #define PG8_SCHED __builtin_amdgcn_sched_barrier(0)
;     __device__ __forceinline__ void operator()(const f32x4 (&acc)[2][2][4][2], const Unit& u, int wr, int wc, int fr, int fq, const bool reuse, PG8_LAS float* rscr, PG8_LAS const float* gains) const {
;     ...
;                 for (int ai = 0; ai < 2; ++ai)
; #pragma unroll
;                     for (int m = 0; m < 4; ++m) { const int r = u.pm * BM + ai * HALF + wr * 64 + m * 16 + fr; rs4[ai][m] = *(const f32x4*)(rs + (size_t)(row_base + r) * 16 + 4 * fq); }
;     ...
;             PG8_WAIT_V(8); PG8_WAIT_L(0); PG8_BAR; PG8_MMA(0, 0, At, B0); PG8_MMA(0, 1, At, B1); PG8_BAR; PG8_SCHED;
;             PG8_LDA(At, 0, 1); PG8_STAGE(PG8_SB(0, 0), b2, voffB); PG8_STAGE(PG8_SB(0, 1), b2 + hstepB, voffB); PG8_STAGE(PG8_SA(0, 0), a2, voffA);
;             PG8_WAIT_V(8); PG8_WAIT_L(0); PG8_BAR; PG8_MMA(1, 0, At, B0); PG8_MMA(1, 1, At, B1); PG8_BAR; PG8_SCHED;
.Lpkb_da:
	s_barrier
	v_mfma_f32_16x16x32_f16 v[132:135], v[112:115], v[160:163], v[132:135]
	v_mfma_f32_16x16x32_f16 v[128:131], v[120:123], v[160:163], v[128:131]
	v_mfma_f32_16x16x32_f16 v[100:103], v[112:115], v[168:171], v[100:103]
	v_mfma_f32_16x16x32_f16 v[96:99], v[120:123], v[168:171], v[96:99]
	v_mfma_f32_16x16x32_f16 v[84:87], v[112:115], v[202:205], v[84:87]
	v_mfma_f32_16x16x32_f16 v[80:83], v[120:123], v[202:205], v[80:83]
	v_mfma_f32_16x16x32_f16 v[68:71], v[112:115], v[210:213], v[68:71]
	v_mfma_f32_16x16x32_f16 v[64:67], v[120:123], v[210:213], v[64:67]
	v_mfma_f32_16x16x32_f16 v[132:135], v[116:119], v[164:167], v[132:135]
	v_mfma_f32_16x16x32_f16 v[128:131], v[124:127], v[164:167], v[128:131]
	v_mfma_f32_16x16x32_f16 v[100:103], v[116:119], v[192:195], v[100:103]
	v_mfma_f32_16x16x32_f16 v[96:99], v[124:127], v[192:195], v[96:99]
	v_mfma_f32_16x16x32_f16 v[84:87], v[116:119], v[206:209], v[84:87]
	v_mfma_f32_16x16x32_f16 v[80:83], v[124:127], v[206:209], v[80:83]
	v_mfma_f32_16x16x32_f16 v[68:71], v[116:119], v[214:217], v[68:71]
	v_mfma_f32_16x16x32_f16 v[64:67], v[124:127], v[214:217], v[64:67]
	v_mfma_f32_16x16x32_f16 v[140:143], v[144:147], v[160:163], v[140:143]
	v_mfma_f32_16x16x32_f16 v[136:139], v[152:155], v[160:163], v[136:139]
	v_mfma_f32_16x16x32_f16 v[108:111], v[144:147], v[168:171], v[108:111]
	v_mfma_f32_16x16x32_f16 v[104:107], v[152:155], v[168:171], v[104:107]
	v_mfma_f32_16x16x32_f16 v[92:95], v[144:147], v[202:205], v[92:95]
	v_mfma_f32_16x16x32_f16 v[88:91], v[152:155], v[202:205], v[88:91]
	v_mfma_f32_16x16x32_f16 v[76:79], v[144:147], v[210:213], v[76:79]
	v_mfma_f32_16x16x32_f16 v[72:75], v[152:155], v[210:213], v[72:75]
	v_mfma_f32_16x16x32_f16 v[140:143], v[148:151], v[164:167], v[140:143]
	v_mfma_f32_16x16x32_f16 v[136:139], v[156:159], v[164:167], v[136:139]
	v_mfma_f32_16x16x32_f16 v[108:111], v[148:151], v[192:195], v[108:111]
	v_mfma_f32_16x16x32_f16 v[104:107], v[156:159], v[192:195], v[104:107]
	v_mfma_f32_16x16x32_f16 v[92:95], v[148:151], v[206:209], v[92:95]
	v_mfma_f32_16x16x32_f16 v[88:91], v[156:159], v[206:209], v[88:91]
	v_mfma_f32_16x16x32_f16 v[76:79], v[148:151], v[214:217], v[76:79]
	v_mfma_f32_16x16x32_f16 v[72:75], v[156:159], v[214:217], v[72:75]
	s_barrier
	s_add_i32 s57, s51, s28
	v_lshl_add_u64 v[218:219], s[22:23], 0, v[174:175]
	s_mov_b32 m0, s57
	ds_read_b128 v[160:163], v200 offset:16384
	ds_read_b128 v[164:167], v200 offset:17408
	ds_read_b128 v[168:171], v200 offset:18432
	ds_read_b128 v[192:195], v200 offset:19456
	ds_read_b128 v[202:205], v200 offset:20480
	ds_read_b128 v[206:209], v200 offset:21504
	ds_read_b128 v[210:213], v200 offset:22528
	ds_read_b128 v[214:217], v200 offset:23552
	global_load_lds_dwordx4 v[218:219], off
	s_add_i32 m0, s57, 0x2000
	s_add_u32 s58, s22, 0x10000
	v_lshl_add_u64 v[220:221], s[22:23], 0, v[178:179]
	s_addc_u32 s59, s23, 0
	s_add_i32 s57, s52, s28
	global_load_lds_dwordx4 v[220:221], off
	v_lshl_add_u64 v[222:223], s[58:59], 0, v[174:175]
	s_mov_b32 m0, s57
	v_lshl_add_u64 v[224:225], s[26:27], 0, v[176:177]
	global_load_lds_dwordx4 v[222:223], off
	s_add_i32 m0, s57, 0x2000
	v_lshl_add_u64 v[222:223], s[58:59], 0, v[178:179]
	global_load_lds_dwordx4 v[222:223], off
	s_mov_b32 m0, s29
	v_lshl_add_u64 v[222:223], s[26:27], 0, v[172:173]
	global_load_lds_dwordx4 v[222:223], off
	s_mov_b32 m0, s41
	s_nop 0
	global_load_lds_dwordx4 v[224:225], off
	s_cmp_eq_u32 s56, 10
	s_cbranch_scc0 .Lrs_n
	s_cmp_lg_u32 s54, s38
	s_cbranch_scc0 .Lrs_n
	s_bitset1_b32 s101, 17
	s_lshl_b32 s32, s54, 8
	s_add_i32 s32, s32, s45
	s_bfe_u32 vcc_lo, s29, 0x2000a
	s_and_b32 vcc_hi, vcc_lo, 1
	s_lshl_b32 vcc_hi, vcc_hi, 5
	s_lshr_b32 m0, vcc_lo, 1
	s_lshl_b32 m0, m0, 7
	s_add_i32 vcc_hi, vcc_hi, m0
	s_add_i32 s32, s32, vcc_hi
	v_or_b32_e32 v228, s32, v196
	v_add_u32_e32 v230, 16, v228
	v_lshlrev_b32_e32 v228, 6, v228
	v_lshlrev_b32_e32 v230, 6, v230
	v_mov_b32_e32 v229, 0
	v_mov_b32_e32 v231, 0
	v_lshl_add_u64 v[228:229], v[228:229], 0, v[182:183]
	v_lshl_add_u64 v[230:231], v[230:231], 0, v[182:183]
	s_lshl_b32 vcc_lo, vcc_lo, 11
	s_lshr_b32 vcc_hi, s29, 12
	s_lshl_b32 vcc_hi, vcc_hi, 13
	s_add_i32 vcc_lo, vcc_lo, vcc_hi
	s_add_i32 m0, vcc_lo, 0x22000
	s_nop 0
	global_load_lds_dwordx4 v[228:229], off
	s_add_i32 m0, m0, 0x400
	s_nop 0
	global_load_lds_dwordx4 v[230:231], off
.Lrs_n:
	s_bfe_u32 vcc_lo, s101, 0x20010
	s_cmp_eq_u32 vcc_lo, 0
	s_cbranch_scc1 .Lpkb_w8b
	s_cmp_eq_u32 vcc_lo, 1
	s_cbranch_scc1 .Lpkb_w9b
	s_cmp_eq_u32 vcc_lo, 2
	s_cbranch_scc1 .Lpkb_w10b
	s_waitcnt vmcnt(11) lgkmcnt(0)
	s_branch .Lpkb_db
.Lpkb_w10b:
	s_waitcnt vmcnt(10) lgkmcnt(0)
	s_branch .Lpkb_db

; #define PG8_STAGE(bufoff, gbase, voff) do { _Pragma("unroll") for (int _i = 0; _i < 2; ++_i) \
;         __builtin_amdgcn_global_load_lds((const unsigned*)((const char*)(gbase) + (voff)[_i]), (PG8_LAS unsigned*)(lds + (bufoff) + ldsw + _i * 8192), 16, 0, 0); } while (0)
; #define PG8_LDA(dst, b, h) do { _Pragma("unroll") for (int m = 0; m < 4; ++m) _Pragma("unroll") for (int k = 0; k < 2; ++k) dst[m][k] = *(const PG8_LAS bf16x8*)(lds + PG8_SA(b, h) + aoff + m * 2048 + k * 1024); } while (0)
; #define PG8_LDB(dst, b, h) do { _Pragma("unroll") for (int n = 0; n < 2; ++n) _Pragma("unroll") for (int k = 0; k < 2; ++k) dst[n][k] = *(const PG8_LAS bf16x8*)(lds + PG8_SB(b, h) + boff + n * 2048 + k * 1024); } while (0)
; #define PG8_WAIT_V(n) asm volatile("s_waitcnt vmcnt(" #n ")" ::: "memory")
; #define PG8_WAIT_L(n) asm volatile("s_waitcnt lgkmcnt(" #n ")" ::: "memory")
; #define PG8_BAR __builtin_amdgcn_s_barrier()
; #define PG8_SCHED __builtin_amdgcn_sched_barrier(0)
;     ...
;             PG8_WAIT_V(8); PG8_WAIT_L(0); PG8_BAR; PG8_MMA(1, 0, At, B0); PG8_MMA(1, 1, At, B1); PG8_BAR; PG8_SCHED;
;             PG8_LDB(B0, 1, 0); PG8_LDB(B1, 1, 1); PG8_SCHED; PG8_LDA(At, 1, 0); PG8_STAGE(PG8_SA(0, 1), a2 + hstep, voffA);
;             PG8_WAIT_V(8); PG8_WAIT_L(0); PG8_BAR; PG8_MMA(0, 0, At, B0); PG8_MMA(0, 1, At, B1); PG8_BAR; PG8_SCHED;
.Lpkb_db:
	s_barrier
	v_mfma_f32_16x16x32_f16 v[52:55], v[112:115], v[160:163], v[52:55]
	v_mfma_f32_16x16x32_f16 v[48:51], v[120:123], v[160:163], v[48:51]
	v_mfma_f32_16x16x32_f16 v[36:39], v[112:115], v[168:171], v[36:39]
	v_mfma_f32_16x16x32_f16 v[32:35], v[120:123], v[168:171], v[32:35]
	v_mfma_f32_16x16x32_f16 v[20:23], v[112:115], v[202:205], v[20:23]
	v_mfma_f32_16x16x32_f16 v[16:19], v[120:123], v[202:205], v[16:19]
	v_mfma_f32_16x16x32_f16 v[4:7], v[112:115], v[210:213], v[4:7]
	v_mfma_f32_16x16x32_f16 v[0:3], v[120:123], v[210:213], v[0:3]
	v_mfma_f32_16x16x32_f16 v[52:55], v[116:119], v[164:167], v[52:55]
	v_mfma_f32_16x16x32_f16 v[48:51], v[124:127], v[164:167], v[48:51]
	v_mfma_f32_16x16x32_f16 v[36:39], v[116:119], v[192:195], v[36:39]
	v_mfma_f32_16x16x32_f16 v[32:35], v[124:127], v[192:195], v[32:35]
	v_mfma_f32_16x16x32_f16 v[20:23], v[116:119], v[206:209], v[20:23]
	v_mfma_f32_16x16x32_f16 v[16:19], v[124:127], v[206:209], v[16:19]
	v_mfma_f32_16x16x32_f16 v[4:7], v[116:119], v[214:217], v[4:7]
	v_mfma_f32_16x16x32_f16 v[0:3], v[124:127], v[214:217], v[0:3]
	v_mfma_f32_16x16x32_f16 v[60:63], v[144:147], v[160:163], v[60:63]
	v_mfma_f32_16x16x32_f16 v[56:59], v[152:155], v[160:163], v[56:59]
	v_mfma_f32_16x16x32_f16 v[44:47], v[144:147], v[168:171], v[44:47]
	v_mfma_f32_16x16x32_f16 v[40:43], v[152:155], v[168:171], v[40:43]
	v_mfma_f32_16x16x32_f16 v[28:31], v[144:147], v[202:205], v[28:31]
	v_mfma_f32_16x16x32_f16 v[24:27], v[152:155], v[202:205], v[24:27]
	v_mfma_f32_16x16x32_f16 v[12:15], v[144:147], v[210:213], v[12:15]
	v_mfma_f32_16x16x32_f16 v[8:11], v[152:155], v[210:213], v[8:11]
	v_mfma_f32_16x16x32_f16 v[60:63], v[148:151], v[164:167], v[60:63]
	v_mfma_f32_16x16x32_f16 v[56:59], v[156:159], v[164:167], v[56:59]
	v_mfma_f32_16x16x32_f16 v[44:47], v[148:151], v[192:195], v[44:47]
	v_mfma_f32_16x16x32_f16 v[40:43], v[156:159], v[192:195], v[40:43]
	v_mfma_f32_16x16x32_f16 v[28:31], v[148:151], v[206:209], v[28:31]
	v_mfma_f32_16x16x32_f16 v[24:27], v[156:159], v[206:209], v[24:27]
	v_mfma_f32_16x16x32_f16 v[12:15], v[148:151], v[214:217], v[12:15]
	v_mfma_f32_16x16x32_f16 v[8:11], v[156:159], v[214:217], v[8:11]
	s_barrier
	s_add_i32 s57, 0, 0x18000
	s_add_i32 s58, 0, 0x1c000
	v_add_u32_e32 v124, s57, v197
	v_add_u32_e32 v156, s58, v197
	ds_read_b128 v[112:115], v124
	ds_read_b128 v[116:119], v124 offset:1024
	ds_read_b128 v[120:123], v124 offset:2048
	ds_read_b128 v[124:127], v124 offset:3072
	ds_read_b128 v[144:147], v156
	ds_read_b128 v[148:151], v156 offset:1024
	ds_read_b128 v[152:155], v156 offset:2048
	ds_read_b128 v[156:159], v156 offset:3072
	s_add_u32 s26, s26, 0x40000
	s_addc_u32 s27, s27, 0
	s_mov_b32 m0, s42
	v_lshl_add_u64 v[226:227], s[26:27], 0, v[172:173]
	ds_read_b128 v[160:163], v200 offset:32768
	ds_read_b128 v[164:167], v200 offset:33792
	ds_read_b128 v[168:171], v200 offset:34816
	ds_read_b128 v[192:195], v200 offset:35840
	ds_read_b128 v[202:205], v200 offset:36864
	ds_read_b128 v[206:209], v200 offset:37888
	ds_read_b128 v[210:213], v200 offset:38912
	ds_read_b128 v[214:217], v200 offset:39936
	global_load_lds_dwordx4 v[226:227], off
	s_mov_b32 m0, s43
	v_lshl_add_u64 v[226:227], s[26:27], 0, v[176:177]
	global_load_lds_dwordx4 v[226:227], off
	s_bfe_u32 vcc_lo, s101, 0x20010
	s_cmp_eq_u32 vcc_lo, 0
	s_cbranch_scc1 .Lpkb_w8c
	s_cmp_eq_u32 vcc_lo, 1
	s_cbranch_scc1 .Lpkb_w9c
	s_cmp_eq_u32 vcc_lo, 2
	s_cbranch_scc1 .Lpkb_w10c
	s_waitcnt vmcnt(11) lgkmcnt(0)
	s_branch .Lpkb_dc

; #define PG8_STAGE(bufoff, gbase, voff) do { _Pragma("unroll") for (int _i = 0; _i < 2; ++_i) \
;         __builtin_amdgcn_global_load_lds((const unsigned*)((const char*)(gbase) + (voff)[_i]), (PG8_LAS unsigned*)(lds + (bufoff) + ldsw + _i * 8192), 16, 0, 0); } while (0)
; #define PG8_LDA(dst, b, h) do { _Pragma("unroll") for (int m = 0; m < 4; ++m) _Pragma("unroll") for (int k = 0; k < 2; ++k) dst[m][k] = *(const PG8_LAS bf16x8*)(lds + PG8_SA(b, h) + aoff + m * 2048 + k * 1024); } while (0)
; #define PG8_WAIT_V(n) asm volatile("s_waitcnt vmcnt(" #n ")" ::: "memory")
; #define PG8_WAIT_L(n) asm volatile("s_waitcnt lgkmcnt(" #n ")" ::: "memory")
; #define PG8_BAR __builtin_amdgcn_s_barrier()
; #define PG8_SCHED __builtin_amdgcn_sched_barrier(0)
;     ...
;             PG8_WAIT_V(8); PG8_WAIT_L(0); PG8_BAR; PG8_MMA(0, 0, At, B0); PG8_MMA(0, 1, At, B1); PG8_BAR; PG8_SCHED;
;             PG8_LDA(At, 1, 1); PG8_STAGE(PG8_SB(1, 0), b3, voffB); PG8_STAGE(PG8_SB(1, 1), b3 + hstepB, voffB); PG8_STAGE(PG8_SA(1, 0), a3, voffA);
;             PG8_WAIT_V(8); PG8_WAIT_L(0); PG8_BAR; PG8_MMA(1, 0, At, B0); PG8_MMA(1, 1, At, B1); PG8_BAR; PG8_SCHED;
.Lpkb_dc:
	s_barrier
	v_mfma_f32_16x16x32_f16 v[132:135], v[112:115], v[160:163], v[132:135]
	v_mfma_f32_16x16x32_f16 v[128:131], v[120:123], v[160:163], v[128:131]
	v_mfma_f32_16x16x32_f16 v[100:103], v[112:115], v[168:171], v[100:103]
	v_mfma_f32_16x16x32_f16 v[96:99], v[120:123], v[168:171], v[96:99]
	v_mfma_f32_16x16x32_f16 v[84:87], v[112:115], v[202:205], v[84:87]
	v_mfma_f32_16x16x32_f16 v[80:83], v[120:123], v[202:205], v[80:83]
	v_mfma_f32_16x16x32_f16 v[68:71], v[112:115], v[210:213], v[68:71]
	v_mfma_f32_16x16x32_f16 v[64:67], v[120:123], v[210:213], v[64:67]
	v_mfma_f32_16x16x32_f16 v[132:135], v[116:119], v[164:167], v[132:135]
	v_mfma_f32_16x16x32_f16 v[128:131], v[124:127], v[164:167], v[128:131]
	v_mfma_f32_16x16x32_f16 v[100:103], v[116:119], v[192:195], v[100:103]
	v_mfma_f32_16x16x32_f16 v[96:99], v[124:127], v[192:195], v[96:99]
	v_mfma_f32_16x16x32_f16 v[84:87], v[116:119], v[206:209], v[84:87]
	v_mfma_f32_16x16x32_f16 v[80:83], v[124:127], v[206:209], v[80:83]
	v_mfma_f32_16x16x32_f16 v[68:71], v[116:119], v[214:217], v[68:71]
	v_mfma_f32_16x16x32_f16 v[64:67], v[124:127], v[214:217], v[64:67]
	v_mfma_f32_16x16x32_f16 v[140:143], v[144:147], v[160:163], v[140:143]
	v_mfma_f32_16x16x32_f16 v[136:139], v[152:155], v[160:163], v[136:139]
	v_mfma_f32_16x16x32_f16 v[108:111], v[144:147], v[168:171], v[108:111]
	v_mfma_f32_16x16x32_f16 v[104:107], v[152:155], v[168:171], v[104:107]
	v_mfma_f32_16x16x32_f16 v[92:95], v[144:147], v[202:205], v[92:95]
	v_mfma_f32_16x16x32_f16 v[88:91], v[152:155], v[202:205], v[88:91]
	v_mfma_f32_16x16x32_f16 v[76:79], v[144:147], v[210:213], v[76:79]
	v_mfma_f32_16x16x32_f16 v[72:75], v[152:155], v[210:213], v[72:75]
	v_mfma_f32_16x16x32_f16 v[140:143], v[148:151], v[164:167], v[140:143]
	v_mfma_f32_16x16x32_f16 v[136:139], v[156:159], v[164:167], v[136:139]
	v_mfma_f32_16x16x32_f16 v[108:111], v[148:151], v[192:195], v[108:111]
	v_mfma_f32_16x16x32_f16 v[104:107], v[156:159], v[192:195], v[104:107]
	v_mfma_f32_16x16x32_f16 v[92:95], v[148:151], v[206:209], v[92:95]
	v_mfma_f32_16x16x32_f16 v[88:91], v[156:159], v[206:209], v[88:91]
	v_mfma_f32_16x16x32_f16 v[76:79], v[148:151], v[214:217], v[76:79]
	v_mfma_f32_16x16x32_f16 v[72:75], v[156:159], v[214:217], v[72:75]
	s_barrier
	s_add_i32 s26, s57, s28
	v_lshl_add_u64 v[218:219], v[218:219], 0, s[10:11]
	s_mov_b32 m0, s26
	ds_read_b128 v[160:163], v200 offset:49152
	ds_read_b128 v[164:167], v200 offset:50176
	ds_read_b128 v[168:171], v200 offset:51200
	ds_read_b128 v[192:195], v200 offset:52224
	ds_read_b128 v[202:205], v200 offset:53248
	ds_read_b128 v[206:209], v200 offset:54272
	ds_read_b128 v[210:213], v200 offset:55296
	ds_read_b128 v[214:217], v200 offset:56320
	global_load_lds_dwordx4 v[218:219], off
	s_add_i32 m0, s26, 0x2000
	s_add_u32 s22, s22, 0x10080
	v_lshl_add_u64 v[218:219], v[220:221], 0, s[10:11]
	s_addc_u32 s23, s23, 0
	s_add_i32 s26, s58, s28
	global_load_lds_dwordx4 v[218:219], off
	s_mov_b32 m0, s26
	v_lshl_add_u64 v[218:219], s[22:23], 0, v[174:175]
	global_load_lds_dwordx4 v[218:219], off
	s_add_i32 m0, s26, 0x2000
	v_lshl_add_u64 v[218:219], s[22:23], 0, v[178:179]
	global_load_lds_dwordx4 v[218:219], off
	s_mov_b32 m0, s48
	v_lshl_add_u64 v[218:219], v[222:223], 0, s[10:11]
	global_load_lds_dwordx4 v[218:219], off
	s_mov_b32 m0, s49
	v_lshl_add_u64 v[218:219], v[224:225], 0, s[10:11]
	global_load_lds_dwordx4 v[218:219], off
	s_bitcmp1_b32 s101, 17
	s_cbranch_scc0 .Lpkb_w8e
	s_waitcnt vmcnt(10) lgkmcnt(0)
	s_branch .Lpkb_de

; #define PG8_WAIT_V(n) asm volatile("s_waitcnt vmcnt(" #n ")" ::: "memory")
; #define PG8_WAIT_L(n) asm volatile("s_waitcnt lgkmcnt(" #n ")" ::: "memory")
; #define PG8_BAR __builtin_amdgcn_s_barrier()
; #define PG8_SCHED __builtin_amdgcn_sched_barrier(0)
;     ...
;             PG8_WAIT_V(8); PG8_WAIT_L(0); PG8_BAR; PG8_MMA(1, 0, At, B0); PG8_MMA(1, 1, At, B1); PG8_BAR; PG8_SCHED;
.Lpkb_de:
	s_barrier
	v_mfma_f32_16x16x32_f16 v[52:55], v[112:115], v[160:163], v[52:55]
	v_mfma_f32_16x16x32_f16 v[48:51], v[120:123], v[160:163], v[48:51]
	v_mfma_f32_16x16x32_f16 v[36:39], v[112:115], v[168:171], v[36:39]
	v_mfma_f32_16x16x32_f16 v[32:35], v[120:123], v[168:171], v[32:35]
	v_mfma_f32_16x16x32_f16 v[20:23], v[112:115], v[202:205], v[20:23]
	v_mfma_f32_16x16x32_f16 v[16:19], v[120:123], v[202:205], v[16:19]
	v_mfma_f32_16x16x32_f16 v[4:7], v[112:115], v[210:213], v[4:7]
	v_mfma_f32_16x16x32_f16 v[0:3], v[120:123], v[210:213], v[0:3]
	v_mfma_f32_16x16x32_f16 v[52:55], v[116:119], v[164:167], v[52:55]
	v_mfma_f32_16x16x32_f16 v[48:51], v[124:127], v[164:167], v[48:51]
	v_mfma_f32_16x16x32_f16 v[36:39], v[116:119], v[192:195], v[36:39]
	v_mfma_f32_16x16x32_f16 v[32:35], v[124:127], v[192:195], v[32:35]
	v_mfma_f32_16x16x32_f16 v[20:23], v[116:119], v[206:209], v[20:23]
	v_mfma_f32_16x16x32_f16 v[16:19], v[124:127], v[206:209], v[16:19]
	v_mfma_f32_16x16x32_f16 v[4:7], v[116:119], v[214:217], v[4:7]
	v_mfma_f32_16x16x32_f16 v[0:3], v[124:127], v[214:217], v[0:3]
	v_mfma_f32_16x16x32_f16 v[60:63], v[144:147], v[160:163], v[60:63]
	v_mfma_f32_16x16x32_f16 v[56:59], v[152:155], v[160:163], v[56:59]
	v_mfma_f32_16x16x32_f16 v[44:47], v[144:147], v[168:171], v[44:47]
	v_mfma_f32_16x16x32_f16 v[40:43], v[152:155], v[168:171], v[40:43]
	v_mfma_f32_16x16x32_f16 v[28:31], v[144:147], v[202:205], v[28:31]
	v_mfma_f32_16x16x32_f16 v[24:27], v[152:155], v[202:205], v[24:27]
	v_mfma_f32_16x16x32_f16 v[12:15], v[144:147], v[210:213], v[12:15]
	v_mfma_f32_16x16x32_f16 v[8:11], v[152:155], v[210:213], v[8:11]
	v_mfma_f32_16x16x32_f16 v[60:63], v[148:151], v[164:167], v[60:63]
	v_mfma_f32_16x16x32_f16 v[56:59], v[156:159], v[164:167], v[56:59]
	v_mfma_f32_16x16x32_f16 v[44:47], v[148:151], v[192:195], v[44:47]
	v_mfma_f32_16x16x32_f16 v[40:43], v[156:159], v[192:195], v[40:43]
	v_mfma_f32_16x16x32_f16 v[28:31], v[148:151], v[206:209], v[28:31]
	v_mfma_f32_16x16x32_f16 v[24:27], v[156:159], v[206:209], v[24:27]
	v_mfma_f32_16x16x32_f16 v[12:15], v[148:151], v[214:217], v[12:15]
	v_mfma_f32_16x16x32_f16 v[8:11], v[156:159], v[214:217], v[8:11]
	s_barrier
	s_bitcmp1_b32 s101, 16
	s_cbranch_scc0 .Lpkb_t
	s_sub_u32 s101, s101, 1

; #define PG8_STAGE(bufoff, gbase, voff) do { _Pragma("unroll") for (int _i = 0; _i < 2; ++_i) \
;         __builtin_amdgcn_global_load_lds((const unsigned*)((const char*)(gbase) + (voff)[_i]), (PG8_LAS unsigned*)(lds + (bufoff) + ldsw + _i * 8192), 16, 0, 0); } while (0)
; #define PG8_LDA(dst, b, h) do { _Pragma("unroll") for (int m = 0; m < 4; ++m) _Pragma("unroll") for (int k = 0; k < 2; ++k) dst[m][k] = *(const PG8_LAS bf16x8*)(lds + PG8_SA(b, h) + aoff + m * 2048 + k * 1024); } while (0)
; #define PG8_LDB(dst, b, h) do { _Pragma("unroll") for (int n = 0; n < 2; ++n) _Pragma("unroll") for (int k = 0; k < 2; ++k) dst[n][k] = *(const PG8_LAS bf16x8*)(lds + PG8_SB(b, h) + boff + n * 2048 + k * 1024); } while (0)
; #define PG8_WAIT_V(n) asm volatile("s_waitcnt vmcnt(" #n ")" ::: "memory")
; #define PG8_WAIT_L(n) asm volatile("s_waitcnt lgkmcnt(" #n ")" ::: "memory")
; #define PG8_BAR __builtin_amdgcn_s_barrier()
; #define PG8_SCHED __builtin_amdgcn_sched_barrier(0)
;     ...
;         for (int t = 0; t < nt; t += 2) {
;             const bool last = (t == nt - 2);
;             const char* a1 = cA + (size_t)(t + 1) * kstep;
;             const char* a2 = last ? nA : cA + (size_t)(t + 2) * kstep; const char* b2 = last ? nB : cB + (size_t)(t + 2) * kstep;
;             const char* a3 = a2 + kstep; const char* b3 = b2 + kstep;
;             PG8_LDB(B0, 0, 0); PG8_LDB(B1, 0, 1); PG8_SCHED; PG8_LDA(At, 0, 0); PG8_STAGE(PG8_SA(1, 1), a1 + hstep, voffA);
;             PG8_WAIT_V(8); PG8_WAIT_L(0); PG8_BAR; PG8_MMA(0, 0, At, B0); PG8_MMA(0, 1, At, B1); PG8_BAR; PG8_SCHED;
;             PG8_LDA(At, 0, 1); PG8_STAGE(PG8_SB(0, 0), b2, voffB); PG8_STAGE(PG8_SB(0, 1), b2 + hstepB, voffB); PG8_STAGE(PG8_SA(0, 0), a2, voffA);
.LBB0_732:
	v_add_u32_e32 v158, s37, v152
	v_add_u32_e32 v174, s38, v152
	ds_read_b128 v[128:131], v158
	ds_read_b128 v[148:151], v158 offset:1024
	ds_read_b128 v[154:157], v158 offset:2048
	ds_read_b128 v[158:161], v158 offset:3072
	ds_read_b128 v[162:165], v174
	ds_read_b128 v[166:169], v174 offset:1024
	ds_read_b128 v[170:173], v174 offset:2048
	ds_read_b128 v[174:177], v174 offset:3072
	s_add_u32 s20, s22, 0xfffc0080
	s_addc_u32 s21, s23, -1
	s_cmp_eq_u32 s53, 12
	s_cselect_b32 s25, s13, s21
	s_cselect_b32 s24, s49, s20
	s_cselect_b32 s21, s11, s52
	s_cselect_b32 s20, s50, s51
	v_lshl_add_u64 v[210:211], s[22:23], 0, v[140:141]
	s_add_i32 m0, s19, 0xc000
	ds_read_b128 v[178:181], v153
	ds_read_b128 v[182:185], v153 offset:1024
	ds_read_b128 v[186:189], v153 offset:2048
	ds_read_b128 v[190:193], v153 offset:3072
	ds_read_b128 v[194:197], v153 offset:4096
	ds_read_b128 v[198:201], v153 offset:5120
	ds_read_b128 v[202:205], v153 offset:6144
	ds_read_b128 v[206:209], v153 offset:7168
	global_load_lds_dwordx4 v[210:211], off
	s_add_i32 m0, s19, 0xe000
	v_lshl_add_u64 v[210:211], s[22:23], 0, v[142:143]
	global_load_lds_dwordx4 v[210:211], off
	s_waitcnt vmcnt(8) lgkmcnt(0)
	s_barrier
	v_mfma_f32_16x16x32_bf16 v[112:115], v[128:131], v[178:181], v[112:115]
	v_mfma_f32_16x16x32_bf16 v[116:119], v[154:157], v[178:181], v[116:119]
	v_mfma_f32_16x16x32_bf16 v[108:111], v[128:131], v[186:189], v[108:111]
	v_mfma_f32_16x16x32_bf16 v[104:107], v[154:157], v[186:189], v[104:107]
	v_mfma_f32_16x16x32_bf16 v[92:95], v[128:131], v[194:197], v[92:95]
	v_mfma_f32_16x16x32_bf16 v[88:91], v[154:157], v[194:197], v[88:91]
	v_mfma_f32_16x16x32_bf16 v[76:79], v[128:131], v[202:205], v[76:79]
	v_mfma_f32_16x16x32_bf16 v[72:75], v[154:157], v[202:205], v[72:75]
	v_mfma_f32_16x16x32_bf16 v[112:115], v[148:151], v[182:185], v[112:115]
	v_mfma_f32_16x16x32_bf16 v[116:119], v[158:161], v[182:185], v[116:119]
	v_mfma_f32_16x16x32_bf16 v[108:111], v[148:151], v[190:193], v[108:111]
	v_mfma_f32_16x16x32_bf16 v[104:107], v[158:161], v[190:193], v[104:107]
	v_mfma_f32_16x16x32_bf16 v[92:95], v[148:151], v[198:201], v[92:95]
	v_mfma_f32_16x16x32_bf16 v[88:91], v[158:161], v[198:201], v[88:91]
	v_mfma_f32_16x16x32_bf16 v[76:79], v[148:151], v[206:209], v[76:79]
	v_mfma_f32_16x16x32_bf16 v[72:75], v[158:161], v[206:209], v[72:75]
	v_mfma_f32_16x16x32_bf16 v[120:123], v[162:165], v[178:181], v[120:123]
	v_mfma_f32_16x16x32_bf16 v[124:127], v[170:173], v[178:181], v[124:127]
	v_mfma_f32_16x16x32_bf16 v[100:103], v[162:165], v[186:189], v[100:103]
	v_mfma_f32_16x16x32_bf16 v[96:99], v[170:173], v[186:189], v[96:99]
	v_mfma_f32_16x16x32_bf16 v[84:87], v[162:165], v[194:197], v[84:87]
	v_mfma_f32_16x16x32_bf16 v[80:83], v[170:173], v[194:197], v[80:83]
	v_mfma_f32_16x16x32_bf16 v[68:71], v[162:165], v[202:205], v[68:71]
	v_mfma_f32_16x16x32_bf16 v[64:67], v[170:173], v[202:205], v[64:67]
	v_mfma_f32_16x16x32_bf16 v[120:123], v[166:169], v[182:185], v[120:123]
	v_mfma_f32_16x16x32_bf16 v[124:127], v[174:177], v[182:185], v[124:127]
	v_mfma_f32_16x16x32_bf16 v[100:103], v[166:169], v[190:193], v[100:103]
	v_mfma_f32_16x16x32_bf16 v[96:99], v[174:177], v[190:193], v[96:99]
	v_mfma_f32_16x16x32_bf16 v[84:87], v[166:169], v[198:201], v[84:87]
	v_mfma_f32_16x16x32_bf16 v[80:83], v[174:177], v[198:201], v[80:83]
	v_mfma_f32_16x16x32_bf16 v[68:71], v[166:169], v[206:209], v[68:71]
	v_mfma_f32_16x16x32_bf16 v[64:67], v[174:177], v[206:209], v[64:67]
	s_barrier
	s_add_i32 s54, s37, s26
	v_lshl_add_u64 v[210:211], s[20:21], 0, v[134:135]
	s_mov_b32 m0, s54
	ds_read_b128 v[178:181], v153 offset:16384
	ds_read_b128 v[182:185], v153 offset:17408
	ds_read_b128 v[186:189], v153 offset:18432
	ds_read_b128 v[190:193], v153 offset:19456
	ds_read_b128 v[194:197], v153 offset:20480
	ds_read_b128 v[198:201], v153 offset:21504
	ds_read_b128 v[202:205], v153 offset:22528
	ds_read_b128 v[206:209], v153 offset:23552
	global_load_lds_dwordx4 v[210:211], off
	s_add_i32 m0, s54, 0x2000
	s_add_u32 s54, s20, 0x40000
	v_lshl_add_u64 v[212:213], s[20:21], 0, v[132:133]
	s_addc_u32 s55, s21, 0
	s_add_i32 s56, s38, s26
	global_load_lds_dwordx4 v[212:213], off
	v_lshl_add_u64 v[214:215], s[54:55], 0, v[134:135]
	s_mov_b32 m0, s56
	v_lshl_add_u64 v[216:217], s[24:25], 0, v[132:133]
	global_load_lds_dwordx4 v[214:215], off
	s_add_i32 m0, s56, 0x2000
	v_lshl_add_u64 v[214:215], s[54:55], 0, v[132:133]
	global_load_lds_dwordx4 v[214:215], off
	s_mov_b32 m0, s19
	v_lshl_add_u64 v[214:215], s[24:25], 0, v[134:135]
	global_load_lds_dwordx4 v[214:215], off
	s_mov_b32 m0, s27
	s_nop 0
	global_load_lds_dwordx4 v[216:217], off
	s_waitcnt vmcnt(8) lgkmcnt(0)
	s_barrier
; #define PG8_STAGE(bufoff, gbase, voff) do { _Pragma("unroll") for (int _i = 0; _i < 2; ++_i) \
;         __builtin_amdgcn_global_load_lds((const unsigned*)((const char*)(gbase) + (voff)[_i]), (PG8_LAS unsigned*)(lds + (bufoff) + ldsw + _i * 8192), 16, 0, 0); } while (0)
; #define PG8_LDA(dst, b, h) do { _Pragma("unroll") for (int m = 0; m < 4; ++m) _Pragma("unroll") for (int k = 0; k < 2; ++k) dst[m][k] = *(const PG8_LAS bf16x8*)(lds + PG8_SA(b, h) + aoff + m * 2048 + k * 1024); } while (0)
; #define PG8_LDB(dst, b, h) do { _Pragma("unroll") for (int n = 0; n < 2; ++n) _Pragma("unroll") for (int k = 0; k < 2; ++k) dst[n][k] = *(const PG8_LAS bf16x8*)(lds + PG8_SB(b, h) + boff + n * 2048 + k * 1024); } while (0)
; #define PG8_WAIT_V(n) asm volatile("s_waitcnt vmcnt(" #n ")" ::: "memory")
; #define PG8_WAIT_L(n) asm volatile("s_waitcnt lgkmcnt(" #n ")" ::: "memory")
; #define PG8_BAR __builtin_amdgcn_s_barrier()
; #define PG8_SCHED __builtin_amdgcn_sched_barrier(0)
;     ...
;             PG8_WAIT_V(8); PG8_WAIT_L(0); PG8_BAR; PG8_MMA(1, 0, At, B0); PG8_MMA(1, 1, At, B1); PG8_BAR; PG8_SCHED;
;             PG8_LDB(B0, 1, 0); PG8_LDB(B1, 1, 1); PG8_SCHED; PG8_LDA(At, 1, 0); PG8_STAGE(PG8_SA(0, 1), a2 + hstep, voffA);
;             PG8_WAIT_V(8); PG8_WAIT_L(0); PG8_BAR; PG8_MMA(0, 0, At, B0); PG8_MMA(0, 1, At, B1); PG8_BAR; PG8_SCHED;
	v_mfma_f32_16x16x32_bf16 v[60:63], v[128:131], v[178:181], v[60:63]
	v_mfma_f32_16x16x32_bf16 v[56:59], v[154:157], v[178:181], v[56:59]
	v_mfma_f32_16x16x32_bf16 v[44:47], v[128:131], v[186:189], v[44:47]
	v_mfma_f32_16x16x32_bf16 v[40:43], v[154:157], v[186:189], v[40:43]
	v_mfma_f32_16x16x32_bf16 v[28:31], v[128:131], v[194:197], v[28:31]
	v_mfma_f32_16x16x32_bf16 v[24:27], v[154:157], v[194:197], v[24:27]
	v_mfma_f32_16x16x32_bf16 v[12:15], v[128:131], v[202:205], v[12:15]
	v_mfma_f32_16x16x32_bf16 v[8:11], v[154:157], v[202:205], v[8:11]
	v_mfma_f32_16x16x32_bf16 v[60:63], v[148:151], v[182:185], v[60:63]
	v_mfma_f32_16x16x32_bf16 v[56:59], v[158:161], v[182:185], v[56:59]
	v_mfma_f32_16x16x32_bf16 v[44:47], v[148:151], v[190:193], v[44:47]
	v_mfma_f32_16x16x32_bf16 v[40:43], v[158:161], v[190:193], v[40:43]
	v_mfma_f32_16x16x32_bf16 v[28:31], v[148:151], v[198:201], v[28:31]
	v_mfma_f32_16x16x32_bf16 v[24:27], v[158:161], v[198:201], v[24:27]
	v_mfma_f32_16x16x32_bf16 v[12:15], v[148:151], v[206:209], v[12:15]
	v_mfma_f32_16x16x32_bf16 v[8:11], v[158:161], v[206:209], v[8:11]
	v_mfma_f32_16x16x32_bf16 v[52:55], v[162:165], v[178:181], v[52:55]
	v_mfma_f32_16x16x32_bf16 v[48:51], v[170:173], v[178:181], v[48:51]
	v_mfma_f32_16x16x32_bf16 v[36:39], v[162:165], v[186:189], v[36:39]
	v_mfma_f32_16x16x32_bf16 v[32:35], v[170:173], v[186:189], v[32:35]
	v_mfma_f32_16x16x32_bf16 v[20:23], v[162:165], v[194:197], v[20:23]
	v_mfma_f32_16x16x32_bf16 v[16:19], v[170:173], v[194:197], v[16:19]
	v_mfma_f32_16x16x32_bf16 v[0:3], v[162:165], v[202:205], v[0:3]
	v_mfma_f32_16x16x32_bf16 v[4:7], v[170:173], v[202:205], v[4:7]
	v_mfma_f32_16x16x32_bf16 v[52:55], v[166:169], v[182:185], v[52:55]
	v_mfma_f32_16x16x32_bf16 v[48:51], v[174:177], v[182:185], v[48:51]
	v_mfma_f32_16x16x32_bf16 v[36:39], v[166:169], v[190:193], v[36:39]
	v_mfma_f32_16x16x32_bf16 v[32:35], v[174:177], v[190:193], v[32:35]
	v_mfma_f32_16x16x32_bf16 v[20:23], v[166:169], v[198:201], v[20:23]
	v_mfma_f32_16x16x32_bf16 v[16:19], v[174:177], v[198:201], v[16:19]
	v_mfma_f32_16x16x32_bf16 v[0:3], v[166:169], v[206:209], v[0:3]
	v_mfma_f32_16x16x32_bf16 v[4:7], v[174:177], v[206:209], v[4:7]
	s_barrier
	s_add_i32 s54, 0, 0x18000
	s_add_i32 s55, 0, 0x1c000
	v_add_u32_e32 v158, s54, v152
	v_add_u32_e32 v174, s55, v152
	ds_read_b128 v[128:131], v158
	ds_read_b128 v[148:151], v158 offset:1024
	ds_read_b128 v[154:157], v158 offset:2048
	ds_read_b128 v[158:161], v158 offset:3072
	ds_read_b128 v[162:165], v174
	ds_read_b128 v[166:169], v174 offset:1024
	ds_read_b128 v[170:173], v174 offset:2048
	ds_read_b128 v[174:177], v174 offset:3072
	s_add_u32 s24, s24, 0x40000
	s_addc_u32 s25, s25, 0
	s_mov_b32 m0, s28
	v_lshl_add_u64 v[218:219], s[24:25], 0, v[134:135]
	ds_read_b128 v[178:181], v153 offset:32768
	ds_read_b128 v[182:185], v153 offset:33792
	ds_read_b128 v[186:189], v153 offset:34816
	ds_read_b128 v[190:193], v153 offset:35840
	ds_read_b128 v[194:197], v153 offset:36864
	ds_read_b128 v[198:201], v153 offset:37888
	ds_read_b128 v[202:205], v153 offset:38912
	ds_read_b128 v[206:209], v153 offset:39936
	global_load_lds_dwordx4 v[218:219], off
	s_mov_b32 m0, s29
	v_lshl_add_u64 v[218:219], s[24:25], 0, v[132:133]
	global_load_lds_dwordx4 v[218:219], off
	s_waitcnt vmcnt(8) lgkmcnt(0)
	s_barrier
	v_mfma_f32_16x16x32_bf16 v[112:115], v[128:131], v[178:181], v[112:115]
	v_mfma_f32_16x16x32_bf16 v[116:119], v[154:157], v[178:181], v[116:119]
	v_mfma_f32_16x16x32_bf16 v[108:111], v[128:131], v[186:189], v[108:111]
	v_mfma_f32_16x16x32_bf16 v[104:107], v[154:157], v[186:189], v[104:107]
	v_mfma_f32_16x16x32_bf16 v[92:95], v[128:131], v[194:197], v[92:95]
	v_mfma_f32_16x16x32_bf16 v[88:91], v[154:157], v[194:197], v[88:91]
	v_mfma_f32_16x16x32_bf16 v[76:79], v[128:131], v[202:205], v[76:79]
	v_mfma_f32_16x16x32_bf16 v[72:75], v[154:157], v[202:205], v[72:75]
	v_mfma_f32_16x16x32_bf16 v[112:115], v[148:151], v[182:185], v[112:115]
	v_mfma_f32_16x16x32_bf16 v[116:119], v[158:161], v[182:185], v[116:119]
	v_mfma_f32_16x16x32_bf16 v[108:111], v[148:151], v[190:193], v[108:111]
	v_mfma_f32_16x16x32_bf16 v[104:107], v[158:161], v[190:193], v[104:107]
	v_mfma_f32_16x16x32_bf16 v[92:95], v[148:151], v[198:201], v[92:95]
	v_mfma_f32_16x16x32_bf16 v[88:91], v[158:161], v[198:201], v[88:91]
	v_mfma_f32_16x16x32_bf16 v[76:79], v[148:151], v[206:209], v[76:79]
	v_mfma_f32_16x16x32_bf16 v[72:75], v[158:161], v[206:209], v[72:75]
	v_mfma_f32_16x16x32_bf16 v[120:123], v[162:165], v[178:181], v[120:123]
	v_mfma_f32_16x16x32_bf16 v[124:127], v[170:173], v[178:181], v[124:127]
	v_mfma_f32_16x16x32_bf16 v[100:103], v[162:165], v[186:189], v[100:103]
	v_mfma_f32_16x16x32_bf16 v[96:99], v[170:173], v[186:189], v[96:99]
	v_mfma_f32_16x16x32_bf16 v[84:87], v[162:165], v[194:197], v[84:87]
	v_mfma_f32_16x16x32_bf16 v[80:83], v[170:173], v[194:197], v[80:83]
	v_mfma_f32_16x16x32_bf16 v[68:71], v[162:165], v[202:205], v[68:71]
	v_mfma_f32_16x16x32_bf16 v[64:67], v[170:173], v[202:205], v[64:67]
	v_mfma_f32_16x16x32_bf16 v[120:123], v[166:169], v[182:185], v[120:123]
	v_mfma_f32_16x16x32_bf16 v[124:127], v[174:177], v[182:185], v[124:127]
	v_mfma_f32_16x16x32_bf16 v[100:103], v[166:169], v[190:193], v[100:103]
	v_mfma_f32_16x16x32_bf16 v[96:99], v[174:177], v[190:193], v[96:99]
	v_mfma_f32_16x16x32_bf16 v[84:87], v[166:169], v[198:201], v[84:87]
	v_mfma_f32_16x16x32_bf16 v[80:83], v[174:177], v[198:201], v[80:83]
	v_mfma_f32_16x16x32_bf16 v[68:71], v[166:169], v[206:209], v[68:71]
	v_mfma_f32_16x16x32_bf16 v[64:67], v[174:177], v[206:209], v[64:67]
	s_barrier
; #define PG8_STAGE(bufoff, gbase, voff) do { _Pragma("unroll") for (int _i = 0; _i < 2; ++_i) \
;         __builtin_amdgcn_global_load_lds((const unsigned*)((const char*)(gbase) + (voff)[_i]), (PG8_LAS unsigned*)(lds + (bufoff) + ldsw + _i * 8192), 16, 0, 0); } while (0)
; #define PG8_LDA(dst, b, h) do { _Pragma("unroll") for (int m = 0; m < 4; ++m) _Pragma("unroll") for (int k = 0; k < 2; ++k) dst[m][k] = *(const PG8_LAS bf16x8*)(lds + PG8_SA(b, h) + aoff + m * 2048 + k * 1024); } while (0)
; #define PG8_WAIT_V(n) asm volatile("s_waitcnt vmcnt(" #n ")" ::: "memory")
; #define PG8_WAIT_L(n) asm volatile("s_waitcnt lgkmcnt(" #n ")" ::: "memory")
; #define PG8_BAR __builtin_amdgcn_s_barrier()
; #define PG8_SCHED __builtin_amdgcn_sched_barrier(0)
;     ...
;             PG8_LDA(At, 1, 1); PG8_STAGE(PG8_SB(1, 0), b3, voffB); PG8_STAGE(PG8_SB(1, 1), b3 + hstepB, voffB); PG8_STAGE(PG8_SA(1, 0), a3, voffA);
;             PG8_WAIT_V(8); PG8_WAIT_L(0); PG8_BAR; PG8_MMA(1, 0, At, B0); PG8_MMA(1, 1, At, B1); PG8_BAR; PG8_SCHED;
;         }
	s_add_i32 s24, s54, s26
	v_lshl_add_u64 v[210:211], v[210:211], 0, s[6:7]
	s_mov_b32 m0, s24
	ds_read_b128 v[178:181], v153 offset:49152
	ds_read_b128 v[182:185], v153 offset:50176
	ds_read_b128 v[186:189], v153 offset:51200
	ds_read_b128 v[190:193], v153 offset:52224
	ds_read_b128 v[194:197], v153 offset:53248
	ds_read_b128 v[198:201], v153 offset:54272
	ds_read_b128 v[202:205], v153 offset:55296
	ds_read_b128 v[206:209], v153 offset:56320
	global_load_lds_dwordx4 v[210:211], off
	s_add_i32 m0, s24, 0x2000
	s_add_u32 s20, s20, 0x40080
	v_lshl_add_u64 v[210:211], v[212:213], 0, s[6:7]
	s_addc_u32 s21, s21, 0
	s_add_i32 s24, s55, s26
	global_load_lds_dwordx4 v[210:211], off
	s_mov_b32 m0, s24
	v_lshl_add_u64 v[210:211], s[20:21], 0, v[134:135]
	global_load_lds_dwordx4 v[210:211], off
	s_add_i32 m0, s24, 0x2000
	v_lshl_add_u64 v[210:211], s[20:21], 0, v[132:133]
	global_load_lds_dwordx4 v[210:211], off
	s_mov_b32 m0, s33
	v_lshl_add_u64 v[210:211], v[214:215], 0, s[6:7]
	global_load_lds_dwordx4 v[210:211], off
	s_mov_b32 m0, s34
	v_lshl_add_u64 v[210:211], v[216:217], 0, s[6:7]
	global_load_lds_dwordx4 v[210:211], off
	s_waitcnt vmcnt(8) lgkmcnt(0)
	s_barrier
	v_mfma_f32_16x16x32_bf16 v[60:63], v[128:131], v[178:181], v[60:63]
	v_mfma_f32_16x16x32_bf16 v[56:59], v[154:157], v[178:181], v[56:59]
	v_mfma_f32_16x16x32_bf16 v[44:47], v[128:131], v[186:189], v[44:47]
	v_mfma_f32_16x16x32_bf16 v[40:43], v[154:157], v[186:189], v[40:43]
	v_mfma_f32_16x16x32_bf16 v[28:31], v[128:131], v[194:197], v[28:31]
	v_mfma_f32_16x16x32_bf16 v[24:27], v[154:157], v[194:197], v[24:27]
	v_mfma_f32_16x16x32_bf16 v[12:15], v[128:131], v[202:205], v[12:15]
	v_mfma_f32_16x16x32_bf16 v[8:11], v[154:157], v[202:205], v[8:11]
	v_mfma_f32_16x16x32_bf16 v[60:63], v[148:151], v[182:185], v[60:63]
	v_mfma_f32_16x16x32_bf16 v[56:59], v[158:161], v[182:185], v[56:59]
	v_mfma_f32_16x16x32_bf16 v[44:47], v[148:151], v[190:193], v[44:47]
	v_mfma_f32_16x16x32_bf16 v[40:43], v[158:161], v[190:193], v[40:43]
	v_mfma_f32_16x16x32_bf16 v[28:31], v[148:151], v[198:201], v[28:31]
	v_mfma_f32_16x16x32_bf16 v[24:27], v[158:161], v[198:201], v[24:27]
	v_mfma_f32_16x16x32_bf16 v[12:15], v[148:151], v[206:209], v[12:15]
	v_mfma_f32_16x16x32_bf16 v[8:11], v[158:161], v[206:209], v[8:11]
	v_mfma_f32_16x16x32_bf16 v[52:55], v[162:165], v[178:181], v[52:55]
	v_mfma_f32_16x16x32_bf16 v[48:51], v[170:173], v[178:181], v[48:51]
	v_mfma_f32_16x16x32_bf16 v[36:39], v[162:165], v[186:189], v[36:39]
	v_mfma_f32_16x16x32_bf16 v[32:35], v[170:173], v[186:189], v[32:35]
	v_mfma_f32_16x16x32_bf16 v[20:23], v[162:165], v[194:197], v[20:23]
	v_mfma_f32_16x16x32_bf16 v[16:19], v[170:173], v[194:197], v[16:19]
	v_mfma_f32_16x16x32_bf16 v[0:3], v[162:165], v[202:205], v[0:3]
	v_mfma_f32_16x16x32_bf16 v[4:7], v[170:173], v[202:205], v[4:7]
	v_mfma_f32_16x16x32_bf16 v[52:55], v[166:169], v[182:185], v[52:55]
	v_mfma_f32_16x16x32_bf16 v[48:51], v[174:177], v[182:185], v[48:51]
	v_mfma_f32_16x16x32_bf16 v[36:39], v[166:169], v[190:193], v[36:39]
	v_mfma_f32_16x16x32_bf16 v[32:35], v[174:177], v[190:193], v[32:35]
	v_mfma_f32_16x16x32_bf16 v[20:23], v[166:169], v[198:201], v[20:23]
	v_mfma_f32_16x16x32_bf16 v[16:19], v[174:177], v[198:201], v[16:19]
	v_mfma_f32_16x16x32_bf16 v[0:3], v[166:169], v[206:209], v[0:3]
	v_mfma_f32_16x16x32_bf16 v[4:7], v[174:177], v[206:209], v[4:7]
	s_barrier
	s_add_i32 s53, s53, 2
	s_add_u32 s22, s22, 0x100
	s_addc_u32 s23, s23, 0
	s_add_u32 s51, s51, 0x100
	s_addc_u32 s52, s52, 0
	s_cmp_gt_u32 s53, 13
	s_cbranch_scc0 .LBB0_732
	s_and_b64 vcc, exec, s[8:9]
	s_cbranch_vccz .LBB0_735
	s_barrier
